# strategy: one static s_setprio 1 for waves 4-7 at kernel entry, every per-cluster s_setprio flip deleted
# baseline (speedup 1.0000x reference)
.LBB0_5:
	s_or_b64 exec, exec, s[0:1]
	v_readfirstlane_b32 s0, v196
	s_nop 3
	s_lshr_b32 s0, s0, 8
	s_cmp_eq_u32 s0, 1
	s_cbranch_scc0 .Lprio_done
	s_setprio 1
.Lprio_done:
	v_readlane_b32 s0, v252, 0
	v_readlane_b32 s1, v252, 1
	s_load_dwordx2 s[0:1], s[0:1], 0x290
	s_waitcnt lgkmcnt(0)
	v_writelane_b32 v252, s0, 8
	s_nop 1
	v_writelane_b32 v252, s1, 9
	s_cmp_ge_i32 s0, s1
	s_cbranch_scc0 .LBB0_6
	s_getpc_b64 s[98:99]

.Lres_loop:
	s_waitcnt vmcnt(6)
	s_barrier
	s_add_i32 vcc_hi, s9, 2
	s_cmp_ge_u32 vcc_hi, 3
	s_cselect_b32 vcc_lo, 3, 0
	s_sub_i32 vcc_hi, vcc_hi, vcc_lo
	s_mul_i32 vcc_hi, vcc_hi, 0xc000
	s_add_i32 vcc_hi, vcc_hi, s10
	ds_read_b128 v[154:157], v86
	ds_read_b128 v[158:161], v86 offset:4096
	ds_read_b128 v[162:165], v128 offset:32768
	ds_read_b128 v[166:169], v128 offset:36864
	ds_read_b128 v[66:69], v87
	ds_read_b128 v[70:73], v87 offset:4096
	ds_read_b128 v[74:77], v129 offset:32768
	ds_read_b128 v[78:81], v129 offset:36864
	s_waitcnt lgkmcnt(4)
	v_mfma_f32_32x32x16_bf16 v[50:65], v[154:157], v[162:165], v[50:65]
	s_mov_b32 m0, vcc_hi
	v_mfma_f32_32x32x16_bf16 v[18:33], v[158:161], v[162:165], v[18:33]
	global_load_lds_dwordx4 v82, s[22:23]
	s_add_u32 m0, m0, 0x2000
	v_mfma_f32_32x32x16_bf16 v[34:49], v[154:157], v[166:169], v[34:49]
	global_load_lds_dwordx4 v83, s[22:23]
	s_add_u32 m0, m0, 0x2000
	v_mfma_f32_32x32x16_bf16 v[2:17], v[158:161], v[166:169], v[2:17]
	global_load_lds_dwordx4 v84, s[22:23]
	s_add_u32 m0, m0, 0x2000
	s_nop 0
	global_load_lds_dwordx4 v85, s[22:23]
	s_add_u32 m0, m0, 0x2000
	s_nop 0
	global_load_lds_dwordx4 v82, s[4:5]
	s_add_u32 m0, m0, 0x2000
	s_nop 0
	global_load_lds_dwordx4 v83, s[4:5]
	s_add_u32 s22, s22, 0x80
	s_addc_u32 s23, s23, 0
	s_add_u32 s4, s4, 0x80
	s_addc_u32 s5, s5, 0
	ds_read_b128 v[154:157], v88
	ds_read_b128 v[158:161], v88 offset:4096
	ds_read_b128 v[162:165], v130 offset:32768
	ds_read_b128 v[166:169], v130 offset:36864
	s_waitcnt lgkmcnt(4)
	v_mfma_f32_32x32x16_bf16 v[50:65], v[66:69], v[74:77], v[50:65]
	v_mfma_f32_32x32x16_bf16 v[18:33], v[70:73], v[74:77], v[18:33]
	v_mfma_f32_32x32x16_bf16 v[34:49], v[66:69], v[78:81], v[34:49]
	v_mfma_f32_32x32x16_bf16 v[2:17], v[70:73], v[78:81], v[2:17]
	ds_read_b128 v[66:69], v89
	ds_read_b128 v[70:73], v89 offset:4096
	ds_read_b128 v[74:77], v131 offset:32768
	ds_read_b128 v[78:81], v131 offset:36864
	s_waitcnt lgkmcnt(4)
	v_mfma_f32_32x32x16_bf16 v[50:65], v[154:157], v[162:165], v[50:65]
	v_mfma_f32_32x32x16_bf16 v[18:33], v[158:161], v[162:165], v[18:33]
	v_mfma_f32_32x32x16_bf16 v[34:49], v[154:157], v[166:169], v[34:49]
	v_mfma_f32_32x32x16_bf16 v[2:17], v[158:161], v[166:169], v[2:17]
	s_waitcnt lgkmcnt(0)
	v_mfma_f32_32x32x16_bf16 v[50:65], v[66:69], v[74:77], v[50:65]
	v_mfma_f32_32x32x16_bf16 v[18:33], v[70:73], v[74:77], v[18:33]
	v_mfma_f32_32x32x16_bf16 v[34:49], v[66:69], v[78:81], v[34:49]
	v_mfma_f32_32x32x16_bf16 v[2:17], v[70:73], v[78:81], v[2:17]
	s_add_i32 s9, s9, 1
	s_cmp_eq_u32 s9, 3
	s_cselect_b32 vcc_lo, 0xfffdc000, 0
	s_cselect_b32 s9, 0, s9
	s_add_i32 vcc_lo, vcc_lo, 0xc000
	v_add_u32_e32 v86, vcc_lo, v86
	v_add_u32_e32 v128, vcc_lo, v128
	v_add_u32_e32 v87, vcc_lo, v87
	v_add_u32_e32 v129, vcc_lo, v129
	v_add_u32_e32 v88, vcc_lo, v88
	v_add_u32_e32 v130, vcc_lo, v130
	v_add_u32_e32 v89, vcc_lo, v89
	v_add_u32_e32 v131, vcc_lo, v131
	s_add_i32 s8, s8, -1
	s_cmp_lg_u32 s8, 0
	s_cbranch_scc1 .Lres_loop
	s_waitcnt vmcnt(6)
	s_barrier
	ds_read_b128 v[154:157], v86
	ds_read_b128 v[158:161], v86 offset:4096
	ds_read_b128 v[162:165], v128 offset:32768
	ds_read_b128 v[166:169], v128 offset:36864
	ds_read_b128 v[66:69], v87
	ds_read_b128 v[70:73], v87 offset:4096
	ds_read_b128 v[74:77], v129 offset:32768
	ds_read_b128 v[78:81], v129 offset:36864
	s_waitcnt lgkmcnt(4)
	v_mfma_f32_32x32x16_bf16 v[50:65], v[154:157], v[162:165], v[50:65]
	v_mfma_f32_32x32x16_bf16 v[18:33], v[158:161], v[162:165], v[18:33]
	v_mfma_f32_32x32x16_bf16 v[34:49], v[154:157], v[166:169], v[34:49]
	v_mfma_f32_32x32x16_bf16 v[2:17], v[158:161], v[166:169], v[2:17]
	ds_read_b128 v[154:157], v88
	ds_read_b128 v[158:161], v88 offset:4096
	ds_read_b128 v[162:165], v130 offset:32768
	ds_read_b128 v[166:169], v130 offset:36864
	s_waitcnt lgkmcnt(4)
	v_mfma_f32_32x32x16_bf16 v[50:65], v[66:69], v[74:77], v[50:65]
	v_mfma_f32_32x32x16_bf16 v[18:33], v[70:73], v[74:77], v[18:33]
	v_mfma_f32_32x32x16_bf16 v[34:49], v[66:69], v[78:81], v[34:49]
	v_mfma_f32_32x32x16_bf16 v[2:17], v[70:73], v[78:81], v[2:17]
	ds_read_b128 v[66:69], v89
	ds_read_b128 v[70:73], v89 offset:4096
	ds_read_b128 v[74:77], v131 offset:32768
	ds_read_b128 v[78:81], v131 offset:36864
	s_waitcnt lgkmcnt(4)
	v_mfma_f32_32x32x16_bf16 v[50:65], v[154:157], v[162:165], v[50:65]
	v_mfma_f32_32x32x16_bf16 v[18:33], v[158:161], v[162:165], v[18:33]
	v_mfma_f32_32x32x16_bf16 v[34:49], v[154:157], v[166:169], v[34:49]
	v_mfma_f32_32x32x16_bf16 v[2:17], v[158:161], v[166:169], v[2:17]
	s_waitcnt lgkmcnt(0)
	v_mfma_f32_32x32x16_bf16 v[50:65], v[66:69], v[74:77], v[50:65]
	v_mfma_f32_32x32x16_bf16 v[18:33], v[70:73], v[74:77], v[18:33]
	v_mfma_f32_32x32x16_bf16 v[34:49], v[66:69], v[78:81], v[34:49]
	v_mfma_f32_32x32x16_bf16 v[2:17], v[70:73], v[78:81], v[2:17]
	s_add_i32 s9, s9, 1
	s_cmp_eq_u32 s9, 3
	s_cselect_b32 vcc_lo, 0xfffdc000, 0
	s_cselect_b32 s9, 0, s9
	s_add_i32 vcc_lo, vcc_lo, 0xc000
	v_add_u32_e32 v86, vcc_lo, v86
	v_add_u32_e32 v128, vcc_lo, v128
	v_add_u32_e32 v87, vcc_lo, v87
	v_add_u32_e32 v129, vcc_lo, v129
	v_add_u32_e32 v88, vcc_lo, v88
	v_add_u32_e32 v130, vcc_lo, v130
	v_add_u32_e32 v89, vcc_lo, v89
	v_add_u32_e32 v131, vcc_lo, v131
	s_waitcnt vmcnt(0)
	s_barrier
	ds_read_b128 v[154:157], v86
	ds_read_b128 v[158:161], v86 offset:4096
	ds_read_b128 v[162:165], v128 offset:32768
	ds_read_b128 v[166:169], v128 offset:36864
	ds_read_b128 v[66:69], v87
	ds_read_b128 v[70:73], v87 offset:4096
	ds_read_b128 v[74:77], v129 offset:32768
	ds_read_b128 v[78:81], v129 offset:36864
	s_waitcnt lgkmcnt(4)
	v_mfma_f32_32x32x16_bf16 v[50:65], v[154:157], v[162:165], v[50:65]
	v_mfma_f32_32x32x16_bf16 v[18:33], v[158:161], v[162:165], v[18:33]
	v_mfma_f32_32x32x16_bf16 v[34:49], v[154:157], v[166:169], v[34:49]
	v_mfma_f32_32x32x16_bf16 v[2:17], v[158:161], v[166:169], v[2:17]
	ds_read_b128 v[154:157], v88
	ds_read_b128 v[158:161], v88 offset:4096
	ds_read_b128 v[162:165], v130 offset:32768
	ds_read_b128 v[166:169], v130 offset:36864
	s_waitcnt lgkmcnt(4)
	v_mfma_f32_32x32x16_bf16 v[50:65], v[66:69], v[74:77], v[50:65]
	v_mfma_f32_32x32x16_bf16 v[18:33], v[70:73], v[74:77], v[18:33]
	v_mfma_f32_32x32x16_bf16 v[34:49], v[66:69], v[78:81], v[34:49]
	v_mfma_f32_32x32x16_bf16 v[2:17], v[70:73], v[78:81], v[2:17]
	ds_read_b128 v[66:69], v89
	ds_read_b128 v[70:73], v89 offset:4096
	ds_read_b128 v[74:77], v131 offset:32768
	ds_read_b128 v[78:81], v131 offset:36864
	s_waitcnt lgkmcnt(4)
	v_mfma_f32_32x32x16_bf16 v[50:65], v[154:157], v[162:165], v[50:65]
	v_mfma_f32_32x32x16_bf16 v[18:33], v[158:161], v[162:165], v[18:33]
	v_mfma_f32_32x32x16_bf16 v[34:49], v[154:157], v[166:169], v[34:49]
	v_mfma_f32_32x32x16_bf16 v[2:17], v[158:161], v[166:169], v[2:17]
	s_waitcnt lgkmcnt(0)
	v_mfma_f32_32x32x16_bf16 v[50:65], v[66:69], v[74:77], v[50:65]
	v_mfma_f32_32x32x16_bf16 v[18:33], v[70:73], v[74:77], v[18:33]
	v_mfma_f32_32x32x16_bf16 v[34:49], v[66:69], v[78:81], v[34:49]
	v_mfma_f32_32x32x16_bf16 v[2:17], v[70:73], v[78:81], v[2:17]
	s_barrier
	v_readlane_b32 s4, v254, 0
	v_readlane_b32 s5, v254, 1
	v_readlane_b32 s8, v254, 4
	v_readlane_b32 s9, v254, 5
	v_readlane_b32 s10, v254, 6
	v_readlane_b32 s11, v254, 7
	v_readlane_b32 s12, v254, 8
	v_readlane_b32 s13, v254, 9
	v_readlane_b32 s14, v254, 10
	v_readlane_b32 s15, v254, 11
	v_readlane_b32 s16, v254, 12
	v_readlane_b32 s17, v254, 13
	v_readlane_b32 s18, v254, 14
	v_readlane_b32 s19, v254, 15
	s_nop 7
	v_add_u32_e32 v70, s40, v142
	v_add_u32_e32 v66, 0xfffff000, v70
	v_lshrrev_b32_e32 v66, 11, v66
	s_movk_i32 s4, 0x1800
	v_mad_u32_u24 v76, v66, s4, s4
	s_movk_i32 s4, 0xfff
	v_cmp_lt_i32_e32 vcc, s4, v70
	v_or_b32_e32 v68, s44, v143
	s_nop 0
	v_cndmask_b32_e32 v78, 0, v76, vcc
	v_add_u32_e32 v66, v78, v68
	v_ashrrev_i32_e32 v67, 31, v66
	v_lshl_add_u64 v[66:67], v[66:67], 2, s[28:29]
	s_barrier
	global_load_dword v79, v[66:67], off
	v_readlane_b32 s4, v252, 14
	v_ashrrev_i32_e32 v69, 31, v68
	v_readlane_b32 s5, v252, 15
	v_lshl_add_u64 v[66:67], v[68:69], 2, s[42:43]
	v_mov_b32_e32 v77, 0
	s_and_b64 vcc, exec, s[4:5]
	v_mov_b32_e32 v80, 0
	s_cbranch_vccz .LBB0_96
	global_load_dword v80, v[66:67], off

.Lhyin_loop:
	s_waitcnt vmcnt(6)
	s_barrier
	s_add_i32 vcc_hi, s27, 2
	s_cmp_ge_u32 vcc_hi, 3
	s_cselect_b32 vcc_lo, 3, 0
	s_sub_i32 vcc_hi, vcc_hi, vcc_lo
	s_mul_i32 vcc_hi, vcc_hi, 0xc000
	s_add_i32 vcc_hi, vcc_hi, s30
	ds_read_b128 v[66:69], v102
	ds_read_b128 v[70:73], v102 offset:4096
	ds_read_b128 v[74:77], v106 offset:32768
	ds_read_b128 v[78:81], v106 offset:36864
	ds_read_b128 v[82:85], v103
	ds_read_b128 v[86:89], v103 offset:4096
	ds_read_b128 v[90:93], v107 offset:32768
	ds_read_b128 v[94:97], v107 offset:36864
	s_waitcnt lgkmcnt(4)
	v_mfma_f32_32x32x16_bf16 v[2:17], v[66:69], v[74:77], v[2:17]
	s_mov_b32 m0, vcc_hi
	v_mfma_f32_32x32x16_bf16 v[18:33], v[70:73], v[74:77], v[18:33]
	global_load_lds_dwordx4 v98, s[0:1]
	s_add_u32 m0, m0, 0x2000
	v_mfma_f32_32x32x16_bf16 v[34:49], v[66:69], v[78:81], v[34:49]
	global_load_lds_dwordx4 v99, s[0:1]
	s_add_u32 m0, m0, 0x2000
	v_mfma_f32_32x32x16_bf16 v[50:65], v[70:73], v[78:81], v[50:65]
	global_load_lds_dwordx4 v100, s[0:1]
	s_add_u32 m0, m0, 0x2000
	s_nop 0
	global_load_lds_dwordx4 v101, s[0:1]
	s_add_u32 m0, m0, 0x2000
	s_nop 0
	global_load_lds_dwordx4 v98, s[20:21]
	s_add_u32 m0, m0, 0x2000
	s_nop 0
	global_load_lds_dwordx4 v99, s[20:21]
	s_add_u32 s0, s0, 0x80
	s_addc_u32 s1, s1, 0
	s_add_u32 s20, s20, 0x80
	s_addc_u32 s21, s21, 0
	ds_read_b128 v[66:69], v104
	ds_read_b128 v[70:73], v104 offset:4096
	ds_read_b128 v[74:77], v108 offset:32768
	ds_read_b128 v[78:81], v108 offset:36864
	s_waitcnt lgkmcnt(4)
	v_mfma_f32_32x32x16_bf16 v[2:17], v[82:85], v[90:93], v[2:17]
	v_mfma_f32_32x32x16_bf16 v[18:33], v[86:89], v[90:93], v[18:33]
	v_mfma_f32_32x32x16_bf16 v[34:49], v[82:85], v[94:97], v[34:49]
	v_mfma_f32_32x32x16_bf16 v[50:65], v[86:89], v[94:97], v[50:65]
	ds_read_b128 v[82:85], v105
	ds_read_b128 v[86:89], v105 offset:4096
	ds_read_b128 v[90:93], v109 offset:32768
	ds_read_b128 v[94:97], v109 offset:36864
	s_waitcnt lgkmcnt(4)
	v_mfma_f32_32x32x16_bf16 v[2:17], v[66:69], v[74:77], v[2:17]
	v_mfma_f32_32x32x16_bf16 v[18:33], v[70:73], v[74:77], v[18:33]
	v_mfma_f32_32x32x16_bf16 v[34:49], v[66:69], v[78:81], v[34:49]
	v_mfma_f32_32x32x16_bf16 v[50:65], v[70:73], v[78:81], v[50:65]
	s_waitcnt lgkmcnt(0)
	v_mfma_f32_32x32x16_bf16 v[2:17], v[82:85], v[90:93], v[2:17]
	v_mfma_f32_32x32x16_bf16 v[18:33], v[86:89], v[90:93], v[18:33]
	v_mfma_f32_32x32x16_bf16 v[34:49], v[82:85], v[94:97], v[34:49]
	v_mfma_f32_32x32x16_bf16 v[50:65], v[86:89], v[94:97], v[50:65]
	s_add_i32 s27, s27, 1
	s_cmp_eq_u32 s27, 3
	s_cselect_b32 vcc_lo, 0xfffdc000, 0
	s_cselect_b32 s27, 0, s27
	s_add_i32 vcc_lo, vcc_lo, 0xc000
	v_add_u32_e32 v102, vcc_lo, v102
	v_add_u32_e32 v106, vcc_lo, v106
	v_add_u32_e32 v103, vcc_lo, v103
	v_add_u32_e32 v107, vcc_lo, v107
	v_add_u32_e32 v104, vcc_lo, v104
	v_add_u32_e32 v108, vcc_lo, v108
	v_add_u32_e32 v105, vcc_lo, v105
	v_add_u32_e32 v109, vcc_lo, v109
	s_add_i32 s26, s26, -1
	s_cmp_lg_u32 s26, 0
	s_cbranch_scc1 .Lhyin_loop
	s_waitcnt vmcnt(6)
	s_barrier
	ds_read_b128 v[66:69], v102
	ds_read_b128 v[70:73], v102 offset:4096
	ds_read_b128 v[74:77], v106 offset:32768
	ds_read_b128 v[78:81], v106 offset:36864
	ds_read_b128 v[82:85], v103
	ds_read_b128 v[86:89], v103 offset:4096
	ds_read_b128 v[90:93], v107 offset:32768
	ds_read_b128 v[94:97], v107 offset:36864
	s_waitcnt lgkmcnt(4)
	v_mfma_f32_32x32x16_bf16 v[2:17], v[66:69], v[74:77], v[2:17]
	v_mfma_f32_32x32x16_bf16 v[18:33], v[70:73], v[74:77], v[18:33]
	v_mfma_f32_32x32x16_bf16 v[34:49], v[66:69], v[78:81], v[34:49]
	v_mfma_f32_32x32x16_bf16 v[50:65], v[70:73], v[78:81], v[50:65]
	ds_read_b128 v[66:69], v104
	ds_read_b128 v[70:73], v104 offset:4096
	ds_read_b128 v[74:77], v108 offset:32768
	ds_read_b128 v[78:81], v108 offset:36864
	s_waitcnt lgkmcnt(4)
	v_mfma_f32_32x32x16_bf16 v[2:17], v[82:85], v[90:93], v[2:17]
	v_mfma_f32_32x32x16_bf16 v[18:33], v[86:89], v[90:93], v[18:33]
	v_mfma_f32_32x32x16_bf16 v[34:49], v[82:85], v[94:97], v[34:49]
	v_mfma_f32_32x32x16_bf16 v[50:65], v[86:89], v[94:97], v[50:65]
	ds_read_b128 v[82:85], v105
	ds_read_b128 v[86:89], v105 offset:4096
	ds_read_b128 v[90:93], v109 offset:32768
	ds_read_b128 v[94:97], v109 offset:36864
	s_waitcnt lgkmcnt(4)
	v_mfma_f32_32x32x16_bf16 v[2:17], v[66:69], v[74:77], v[2:17]
	v_mfma_f32_32x32x16_bf16 v[18:33], v[70:73], v[74:77], v[18:33]
	v_mfma_f32_32x32x16_bf16 v[34:49], v[66:69], v[78:81], v[34:49]
	v_mfma_f32_32x32x16_bf16 v[50:65], v[70:73], v[78:81], v[50:65]
	s_waitcnt lgkmcnt(0)
	v_mfma_f32_32x32x16_bf16 v[2:17], v[82:85], v[90:93], v[2:17]
	v_mfma_f32_32x32x16_bf16 v[18:33], v[86:89], v[90:93], v[18:33]
	v_mfma_f32_32x32x16_bf16 v[34:49], v[82:85], v[94:97], v[34:49]
	v_mfma_f32_32x32x16_bf16 v[50:65], v[86:89], v[94:97], v[50:65]
	s_add_i32 s27, s27, 1
	s_cmp_eq_u32 s27, 3
	s_cselect_b32 vcc_lo, 0xfffdc000, 0
	s_cselect_b32 s27, 0, s27
	s_add_i32 vcc_lo, vcc_lo, 0xc000
	v_add_u32_e32 v102, vcc_lo, v102
	v_add_u32_e32 v106, vcc_lo, v106
	v_add_u32_e32 v103, vcc_lo, v103
	v_add_u32_e32 v107, vcc_lo, v107
	v_add_u32_e32 v104, vcc_lo, v104
	v_add_u32_e32 v108, vcc_lo, v108
	v_add_u32_e32 v105, vcc_lo, v105
	v_add_u32_e32 v109, vcc_lo, v109
	s_waitcnt vmcnt(0)
	s_barrier
	ds_read_b128 v[66:69], v102
	ds_read_b128 v[70:73], v102 offset:4096
	ds_read_b128 v[74:77], v106 offset:32768
	ds_read_b128 v[78:81], v106 offset:36864
	ds_read_b128 v[82:85], v103
	ds_read_b128 v[86:89], v103 offset:4096
	ds_read_b128 v[90:93], v107 offset:32768
	ds_read_b128 v[94:97], v107 offset:36864
	s_waitcnt lgkmcnt(4)
	v_mfma_f32_32x32x16_bf16 v[2:17], v[66:69], v[74:77], v[2:17]
	v_mfma_f32_32x32x16_bf16 v[18:33], v[70:73], v[74:77], v[18:33]
	v_mfma_f32_32x32x16_bf16 v[34:49], v[66:69], v[78:81], v[34:49]
	v_mfma_f32_32x32x16_bf16 v[50:65], v[70:73], v[78:81], v[50:65]
	ds_read_b128 v[66:69], v104
	ds_read_b128 v[70:73], v104 offset:4096
	ds_read_b128 v[74:77], v108 offset:32768
	ds_read_b128 v[78:81], v108 offset:36864
	s_waitcnt lgkmcnt(4)
	v_mfma_f32_32x32x16_bf16 v[2:17], v[82:85], v[90:93], v[2:17]
	v_mfma_f32_32x32x16_bf16 v[18:33], v[86:89], v[90:93], v[18:33]
	v_mfma_f32_32x32x16_bf16 v[34:49], v[82:85], v[94:97], v[34:49]
	v_mfma_f32_32x32x16_bf16 v[50:65], v[86:89], v[94:97], v[50:65]
	ds_read_b128 v[82:85], v105
	ds_read_b128 v[86:89], v105 offset:4096
	ds_read_b128 v[90:93], v109 offset:32768
	ds_read_b128 v[94:97], v109 offset:36864
	s_waitcnt lgkmcnt(4)
	v_mfma_f32_32x32x16_bf16 v[2:17], v[66:69], v[74:77], v[2:17]
	v_mfma_f32_32x32x16_bf16 v[18:33], v[70:73], v[74:77], v[18:33]
	v_mfma_f32_32x32x16_bf16 v[34:49], v[66:69], v[78:81], v[34:49]
	v_mfma_f32_32x32x16_bf16 v[50:65], v[70:73], v[78:81], v[50:65]
	s_waitcnt lgkmcnt(0)
	v_mfma_f32_32x32x16_bf16 v[2:17], v[82:85], v[90:93], v[2:17]
	v_mfma_f32_32x32x16_bf16 v[18:33], v[86:89], v[90:93], v[18:33]
	v_mfma_f32_32x32x16_bf16 v[34:49], v[82:85], v[94:97], v[34:49]
	v_mfma_f32_32x32x16_bf16 v[50:65], v[86:89], v[94:97], v[50:65]
	s_barrier
	v_readlane_b32 s5, v254, 1
	v_readlane_b32 s8, v254, 4
	v_readlane_b32 s9, v254, 5
	v_readlane_b32 s10, v254, 6
	v_readlane_b32 s11, v254, 7
	v_readlane_b32 s12, v254, 8
	v_readlane_b32 s13, v254, 9
	v_readlane_b32 s14, v254, 10
	v_readlane_b32 s15, v254, 11
	v_readlane_b32 s16, v254, 12
	v_readlane_b32 s17, v254, 13
	v_readlane_b32 s18, v254, 14
	v_readlane_b32 s19, v254, 15
	s_nop 7
	s_barrier
	s_nop 5
	ds_write2_b32 v119, v2, v34 offset1:32
	ds_write2_b32 v119, v3, v35 offset0:65 offset1:97
	ds_write2_b32 v119, v4, v36 offset0:130 offset1:162
	ds_write2_b32 v119, v5, v37 offset0:195 offset1:227
	v_add_u32_e32 v2, 0x800, v119
	ds_write2_b32 v2, v6, v38 offset0:8 offset1:40
	ds_write2_b32 v2, v7, v39 offset0:73 offset1:105
	ds_write2_b32 v2, v8, v40 offset0:138 offset1:170
	ds_write2_b32 v2, v9, v41 offset0:203 offset1:235
	v_add_u32_e32 v2, 0x1000, v119
	ds_write2_b32 v2, v10, v42 offset0:16 offset1:48
	ds_write2_b32 v2, v11, v43 offset0:81 offset1:113
	ds_write2_b32 v2, v12, v44 offset0:146 offset1:178
	ds_write2_b32 v2, v13, v45 offset0:211 offset1:243
	v_add_u32_e32 v2, 0x1800, v119
	ds_write2_b32 v2, v14, v46 offset0:24 offset1:56
	ds_write2_b32 v2, v15, v47 offset0:89 offset1:121
	ds_write2_b32 v2, v16, v48 offset0:154 offset1:186
	ds_write2_b32 v2, v17, v49 offset0:219 offset1:251
	v_add_u32_e32 v2, 0x2000, v119
	ds_write2_b32 v2, v18, v50 offset0:32 offset1:64
	ds_write2_b32 v2, v19, v51 offset0:97 offset1:129
	ds_write2_b32 v2, v20, v52 offset0:162 offset1:194
	v_add_u32_e32 v2, 0x2200, v119
	ds_write2_b32 v2, v21, v53 offset0:99 offset1:131
	v_add_u32_e32 v2, 0x2800, v119
	v_add_u32_e32 v66, s40, v112
	ds_write2_b32 v2, v22, v54 offset0:40 offset1:72
	ds_write2_b32 v2, v23, v55 offset0:105 offset1:137
	ds_write2_b32 v2, v24, v56 offset0:170 offset1:202
	v_add_u32_e32 v2, 0x2a00, v119
	v_ashrrev_i32_e32 v67, 31, v66
	v_readlane_b32 s4, v254, 23
	ds_write2_b32 v2, v25, v57 offset0:107 offset1:139
	v_add_u32_e32 v2, 0x3000, v119
	v_or_b32_e32 v68, s42, v113
	v_lshlrev_b64 v[70:71], 14, v[66:67]
	v_readlane_b32 s6, v254, 25
	v_readlane_b32 s7, v254, 26
	ds_write2_b32 v2, v26, v58 offset0:48 offset1:80
	ds_write2_b32 v2, v27, v59 offset0:113 offset1:145
	ds_write2_b32 v2, v28, v60 offset0:178 offset1:210
	v_add_u32_e32 v2, 0x3200, v119
	v_lshl_add_u64 v[70:71], s[6:7], 0, v[70:71]
	v_ashrrev_i32_e32 v69, 31, v68
	ds_write2_b32 v2, v29, v61 offset0:115 offset1:147
	v_add_u32_e32 v2, 0x3800, v119
	v_lshl_add_u64 v[68:69], v[68:69], 1, v[70:71]
	ds_write2_b32 v2, v30, v62 offset0:56 offset1:88
	ds_write2_b32 v2, v31, v63 offset0:121 offset1:153
	ds_write2_b32 v2, v32, v64 offset0:186 offset1:218
	v_add_u32_e32 v2, 0x3a00, v119
	s_mov_b32 s26, 1
	ds_write2_b32 v2, v33, v65 offset0:123 offset1:155
	v_lshl_add_u64 v[2:3], v[68:69], 0, v[0:1]
	v_lshl_add_u64 v[4:5], v[66:67], 2, s[28:29]
	s_mov_b32 s27, 0
	s_mov_b64 s[0:1], 0
	v_readlane_b32 s5, v254, 24
	s_waitcnt lgkmcnt(0)
	s_barrier

.LBB0_425:
	v_add_u32_e32 v99, s22, v140
	v_xor_b32_e32 v99, v99, v141
	v_lshlrev_b32_e32 v99, 4, v99
	v_add_u32_e32 v101, v150, v99
	v_add_u32_e32 v99, v151, v99
	ds_read_b128 v[154:157], v101
	ds_read_b128 v[158:161], v101 offset:4096
	ds_read_b128 v[162:165], v99 offset:32768
	ds_read_b128 v[166:169], v99 offset:36864
	s_waitcnt lgkmcnt(1)
	v_mfma_f32_32x32x16_bf16 v[50:65], v[154:157], v[162:165], v[50:65]
	v_mfma_f32_32x32x16_bf16 v[18:33], v[158:161], v[162:165], v[18:33]
	s_waitcnt lgkmcnt(0)
	v_mfma_f32_32x32x16_bf16 v[34:49], v[154:157], v[166:169], v[34:49]
	v_mfma_f32_32x32x16_bf16 v[2:17], v[158:161], v[166:169], v[2:17]
	s_add_i32 s22, s22, 2
	s_cmp_eq_u32 s22, 8
	s_cbranch_scc0 .LBB0_425
	s_barrier
	s_waitcnt vmcnt(5)
	ds_write_b128 v144, v[66:69]
	s_waitcnt vmcnt(4)
	ds_write_b128 v145, v[70:73]
	s_waitcnt vmcnt(3)
	ds_write_b128 v146, v[74:77]
	s_waitcnt vmcnt(2)
	ds_write_b128 v147, v[78:81]
	s_waitcnt vmcnt(1)
	ds_write_b128 v144, v[82:85] offset:32768
	s_waitcnt vmcnt(0)
	ds_write_b128 v145, v[86:89] offset:32768
	global_load_dwordx4 v[66:69], v[128:129], off offset:384
	global_load_dwordx4 v[70:73], v[130:131], off offset:384
	global_load_dwordx4 v[74:77], v[132:133], off offset:384
	global_load_dwordx4 v[78:81], v[134:135], off offset:384
	global_load_dwordx4 v[82:85], v[136:137], off offset:384
	global_load_dwordx4 v[86:89], v[138:139], off offset:384
	s_mov_b32 s22, 0
.LBB0_427:
	v_add_u32_e32 v99, s22, v140
	v_xor_b32_e32 v99, v99, v141
	v_lshlrev_b32_e32 v99, 4, v99
	v_add_u32_e32 v101, v150, v99
	v_add_u32_e32 v99, v152, v99
	ds_read_b128 v[154:157], v101 offset:49152
	ds_read_b128 v[158:161], v101 offset:53248
	ds_read_b128 v[162:165], v99 offset:32768
	ds_read_b128 v[166:169], v99 offset:36864
	s_waitcnt lgkmcnt(1)
	v_mfma_f32_32x32x16_bf16 v[50:65], v[154:157], v[162:165], v[50:65]
	v_mfma_f32_32x32x16_bf16 v[18:33], v[158:161], v[162:165], v[18:33]
	s_waitcnt lgkmcnt(0)
	v_mfma_f32_32x32x16_bf16 v[34:49], v[154:157], v[166:169], v[34:49]
	v_mfma_f32_32x32x16_bf16 v[2:17], v[158:161], v[166:169], v[2:17]
	s_add_i32 s22, s22, 2
	s_cmp_lg_u32 s22, 8
	s_cbranch_scc1 .LBB0_427
	s_barrier
	s_waitcnt vmcnt(5)
	ds_write_b128 v144, v[66:69] offset:49152
	s_waitcnt vmcnt(4)
	ds_write_b128 v145, v[70:73] offset:49152
	s_waitcnt vmcnt(3)
	ds_write_b128 v146, v[74:77] offset:49152
	s_waitcnt vmcnt(2)
	ds_write_b128 v147, v[78:81] offset:49152
	s_waitcnt vmcnt(1)
	ds_write_b128 v148, v[82:85]
	s_waitcnt vmcnt(0)
	ds_write_b128 v149, v[86:89]
	global_load_dwordx4 v[66:69], v[128:129], off offset:512
	global_load_dwordx4 v[70:73], v[130:131], off offset:512
	global_load_dwordx4 v[74:77], v[132:133], off offset:512
	global_load_dwordx4 v[78:81], v[134:135], off offset:512
	global_load_dwordx4 v[82:85], v[136:137], off offset:512
	global_load_dwordx4 v[86:89], v[138:139], off offset:512
	s_mov_b32 s22, 0
.LBB0_429:
	v_add_u32_e32 v99, s22, v140
	v_xor_b32_e32 v99, v99, v141
	v_lshlrev_b32_e32 v99, 4, v99
	v_add_u32_e32 v101, v150, v99
	v_add_u32_e32 v99, v151, v99
	ds_read_b128 v[154:157], v101
	ds_read_b128 v[158:161], v101 offset:4096
	ds_read_b128 v[162:165], v99 offset:32768
	ds_read_b128 v[166:169], v99 offset:36864
	s_waitcnt lgkmcnt(1)
	v_mfma_f32_32x32x16_bf16 v[50:65], v[154:157], v[162:165], v[50:65]
	v_mfma_f32_32x32x16_bf16 v[18:33], v[158:161], v[162:165], v[18:33]
	s_waitcnt lgkmcnt(0)
	v_mfma_f32_32x32x16_bf16 v[34:49], v[154:157], v[166:169], v[34:49]
	v_mfma_f32_32x32x16_bf16 v[2:17], v[158:161], v[166:169], v[2:17]
	s_add_i32 s22, s22, 2
	s_cmp_lg_u32 s22, 8
	s_cbranch_scc1 .LBB0_429
	s_barrier
	s_waitcnt vmcnt(5)
	ds_write_b128 v144, v[66:69]
	s_waitcnt vmcnt(4)
	ds_write_b128 v145, v[70:73]
	s_waitcnt vmcnt(3)
	ds_write_b128 v146, v[74:77]
	s_waitcnt vmcnt(2)
	ds_write_b128 v147, v[78:81]
	s_waitcnt vmcnt(1)
	ds_write_b128 v144, v[82:85] offset:32768
	s_waitcnt vmcnt(0)
	ds_write_b128 v145, v[86:89] offset:32768
	global_load_dwordx4 v[66:69], v[128:129], off offset:640
	global_load_dwordx4 v[70:73], v[130:131], off offset:640
	global_load_dwordx4 v[74:77], v[132:133], off offset:640
	global_load_dwordx4 v[78:81], v[134:135], off offset:640
	global_load_dwordx4 v[82:85], v[136:137], off offset:640
	global_load_dwordx4 v[86:89], v[138:139], off offset:640
	s_mov_b32 s22, 0
.LBB0_431:
	v_add_u32_e32 v99, s22, v140
	v_xor_b32_e32 v99, v99, v141
	v_lshlrev_b32_e32 v99, 4, v99
	v_add_u32_e32 v101, v150, v99
	v_add_u32_e32 v99, v152, v99
	ds_read_b128 v[154:157], v101 offset:49152
	ds_read_b128 v[158:161], v101 offset:53248
	ds_read_b128 v[162:165], v99 offset:32768
	ds_read_b128 v[166:169], v99 offset:36864
	s_waitcnt lgkmcnt(1)
	v_mfma_f32_32x32x16_bf16 v[50:65], v[154:157], v[162:165], v[50:65]
	v_mfma_f32_32x32x16_bf16 v[18:33], v[158:161], v[162:165], v[18:33]
	s_waitcnt lgkmcnt(0)
	v_mfma_f32_32x32x16_bf16 v[34:49], v[154:157], v[166:169], v[34:49]
	v_mfma_f32_32x32x16_bf16 v[2:17], v[158:161], v[166:169], v[2:17]
	s_add_i32 s22, s22, 2
	s_cmp_lg_u32 s22, 8
	s_cbranch_scc1 .LBB0_431
	s_barrier
	s_waitcnt vmcnt(5)
	ds_write_b128 v144, v[66:69] offset:49152
	s_waitcnt vmcnt(4)
	ds_write_b128 v145, v[70:73] offset:49152
	s_waitcnt vmcnt(3)
	ds_write_b128 v146, v[74:77] offset:49152
	s_waitcnt vmcnt(2)
	ds_write_b128 v147, v[78:81] offset:49152
	s_waitcnt vmcnt(1)
	ds_write_b128 v148, v[82:85]
	s_waitcnt vmcnt(0)
	ds_write_b128 v149, v[86:89]
	global_load_dwordx4 v[66:69], v[128:129], off offset:768
	global_load_dwordx4 v[70:73], v[130:131], off offset:768
	global_load_dwordx4 v[74:77], v[132:133], off offset:768
	global_load_dwordx4 v[78:81], v[134:135], off offset:768
	global_load_dwordx4 v[82:85], v[136:137], off offset:768
	global_load_dwordx4 v[86:89], v[138:139], off offset:768
	s_mov_b32 s22, 0
.LBB0_433:
	v_add_u32_e32 v99, s22, v140
	v_xor_b32_e32 v99, v99, v141
	v_lshlrev_b32_e32 v99, 4, v99
	v_add_u32_e32 v101, v150, v99
	v_add_u32_e32 v99, v151, v99
	ds_read_b128 v[154:157], v101
	ds_read_b128 v[158:161], v101 offset:4096
	ds_read_b128 v[162:165], v99 offset:32768
	ds_read_b128 v[166:169], v99 offset:36864
	s_waitcnt lgkmcnt(1)
	v_mfma_f32_32x32x16_bf16 v[50:65], v[154:157], v[162:165], v[50:65]
	v_mfma_f32_32x32x16_bf16 v[18:33], v[158:161], v[162:165], v[18:33]
	s_waitcnt lgkmcnt(0)
	v_mfma_f32_32x32x16_bf16 v[34:49], v[154:157], v[166:169], v[34:49]
	v_mfma_f32_32x32x16_bf16 v[2:17], v[158:161], v[166:169], v[2:17]
	s_add_i32 s22, s22, 2
	s_cmp_lg_u32 s22, 8
	s_cbranch_scc1 .LBB0_433
	s_barrier
	s_waitcnt vmcnt(5)
	ds_write_b128 v144, v[66:69]
	s_waitcnt vmcnt(4)
	ds_write_b128 v145, v[70:73]
	s_waitcnt vmcnt(3)
	ds_write_b128 v146, v[74:77]
	s_waitcnt vmcnt(2)
	ds_write_b128 v147, v[78:81]
	s_waitcnt vmcnt(1)
	ds_write_b128 v144, v[82:85] offset:32768
	s_waitcnt vmcnt(0)
	ds_write_b128 v145, v[86:89] offset:32768
	global_load_dwordx4 v[66:69], v[128:129], off offset:896
	global_load_dwordx4 v[70:73], v[130:131], off offset:896
	global_load_dwordx4 v[74:77], v[132:133], off offset:896
	global_load_dwordx4 v[78:81], v[134:135], off offset:896
	global_load_dwordx4 v[82:85], v[136:137], off offset:896
	global_load_dwordx4 v[86:89], v[138:139], off offset:896
	s_mov_b32 s22, 0
.LBB0_435:
	v_add_u32_e32 v99, s22, v140
	v_xor_b32_e32 v99, v99, v141
	v_lshlrev_b32_e32 v99, 4, v99
	v_add_u32_e32 v101, v150, v99
	v_add_u32_e32 v99, v152, v99
	ds_read_b128 v[154:157], v101 offset:49152
	ds_read_b128 v[158:161], v101 offset:53248
	ds_read_b128 v[162:165], v99 offset:32768
	ds_read_b128 v[166:169], v99 offset:36864
	s_waitcnt lgkmcnt(1)
	v_mfma_f32_32x32x16_bf16 v[50:65], v[154:157], v[162:165], v[50:65]
	v_mfma_f32_32x32x16_bf16 v[18:33], v[158:161], v[162:165], v[18:33]
	s_waitcnt lgkmcnt(0)
	v_mfma_f32_32x32x16_bf16 v[34:49], v[154:157], v[166:169], v[34:49]
	v_mfma_f32_32x32x16_bf16 v[2:17], v[158:161], v[166:169], v[2:17]
	s_add_i32 s22, s22, 2
	s_cmp_lg_u32 s22, 8
	s_cbranch_scc1 .LBB0_435
	s_barrier
	s_waitcnt vmcnt(5)
	ds_write_b128 v144, v[66:69] offset:49152
	s_waitcnt vmcnt(4)
	ds_write_b128 v145, v[70:73] offset:49152
	s_waitcnt vmcnt(3)
	ds_write_b128 v146, v[74:77] offset:49152
	s_waitcnt vmcnt(2)
	ds_write_b128 v147, v[78:81] offset:49152
	s_waitcnt vmcnt(1)
	ds_write_b128 v148, v[82:85]
	s_waitcnt vmcnt(0)
	ds_write_b128 v149, v[86:89]
	global_load_dwordx4 v[66:69], v[128:129], off offset:1024
	global_load_dwordx4 v[70:73], v[130:131], off offset:1024
	global_load_dwordx4 v[74:77], v[132:133], off offset:1024
	global_load_dwordx4 v[78:81], v[134:135], off offset:1024
	global_load_dwordx4 v[82:85], v[136:137], off offset:1024
	global_load_dwordx4 v[86:89], v[138:139], off offset:1024
	s_mov_b32 s22, 0
.LBB0_437:
	v_add_u32_e32 v99, s22, v140
	v_xor_b32_e32 v99, v99, v141
	v_lshlrev_b32_e32 v99, 4, v99
	v_add_u32_e32 v101, v150, v99
	v_add_u32_e32 v99, v151, v99
	ds_read_b128 v[154:157], v101
	ds_read_b128 v[158:161], v101 offset:4096
	ds_read_b128 v[162:165], v99 offset:32768
	ds_read_b128 v[166:169], v99 offset:36864
	s_waitcnt lgkmcnt(1)
	v_mfma_f32_32x32x16_bf16 v[50:65], v[154:157], v[162:165], v[50:65]
	v_mfma_f32_32x32x16_bf16 v[18:33], v[158:161], v[162:165], v[18:33]
	s_waitcnt lgkmcnt(0)
	v_mfma_f32_32x32x16_bf16 v[34:49], v[154:157], v[166:169], v[34:49]
	v_mfma_f32_32x32x16_bf16 v[2:17], v[158:161], v[166:169], v[2:17]
	s_add_i32 s22, s22, 2
	s_cmp_lg_u32 s22, 8
	s_cbranch_scc1 .LBB0_437
	s_barrier
	s_waitcnt vmcnt(5)
	ds_write_b128 v144, v[66:69]
	s_waitcnt vmcnt(4)
	ds_write_b128 v145, v[70:73]
	s_waitcnt vmcnt(3)
	ds_write_b128 v146, v[74:77]
	s_waitcnt vmcnt(2)
	ds_write_b128 v147, v[78:81]
	s_waitcnt vmcnt(1)
	ds_write_b128 v144, v[82:85] offset:32768
	s_waitcnt vmcnt(0)
	ds_write_b128 v145, v[86:89] offset:32768
	global_load_dwordx4 v[66:69], v[128:129], off offset:1152
	global_load_dwordx4 v[70:73], v[130:131], off offset:1152
	global_load_dwordx4 v[74:77], v[132:133], off offset:1152
	global_load_dwordx4 v[78:81], v[134:135], off offset:1152
	global_load_dwordx4 v[82:85], v[136:137], off offset:1152
	global_load_dwordx4 v[86:89], v[138:139], off offset:1152
	s_mov_b32 s22, 0
.LBB0_439:
	v_add_u32_e32 v99, s22, v140
	v_xor_b32_e32 v99, v99, v141
	v_lshlrev_b32_e32 v99, 4, v99
	v_add_u32_e32 v101, v150, v99
	v_add_u32_e32 v99, v152, v99
	ds_read_b128 v[154:157], v101 offset:49152
	ds_read_b128 v[158:161], v101 offset:53248
	ds_read_b128 v[162:165], v99 offset:32768
	ds_read_b128 v[166:169], v99 offset:36864
	s_waitcnt lgkmcnt(1)
	v_mfma_f32_32x32x16_bf16 v[50:65], v[154:157], v[162:165], v[50:65]
	v_mfma_f32_32x32x16_bf16 v[18:33], v[158:161], v[162:165], v[18:33]
	s_waitcnt lgkmcnt(0)
	v_mfma_f32_32x32x16_bf16 v[34:49], v[154:157], v[166:169], v[34:49]
	v_mfma_f32_32x32x16_bf16 v[2:17], v[158:161], v[166:169], v[2:17]
	s_add_i32 s22, s22, 2
	s_cmp_lg_u32 s22, 8
	s_cbranch_scc1 .LBB0_439
	s_barrier
	s_waitcnt vmcnt(5)
	ds_write_b128 v144, v[66:69] offset:49152
	s_waitcnt vmcnt(4)
	ds_write_b128 v145, v[70:73] offset:49152
	s_waitcnt vmcnt(3)
	ds_write_b128 v146, v[74:77] offset:49152
	s_waitcnt vmcnt(2)
	ds_write_b128 v147, v[78:81] offset:49152
	s_waitcnt vmcnt(1)
	ds_write_b128 v148, v[82:85]
	s_waitcnt vmcnt(0)
	ds_write_b128 v149, v[86:89]
	global_load_dwordx4 v[66:69], v[128:129], off offset:1280
	global_load_dwordx4 v[70:73], v[130:131], off offset:1280
	global_load_dwordx4 v[74:77], v[132:133], off offset:1280
	global_load_dwordx4 v[78:81], v[134:135], off offset:1280
	global_load_dwordx4 v[82:85], v[136:137], off offset:1280
	global_load_dwordx4 v[86:89], v[138:139], off offset:1280
	s_mov_b32 s22, 0
.LBB0_441:
	v_add_u32_e32 v99, s22, v140
	v_xor_b32_e32 v99, v99, v141
	v_lshlrev_b32_e32 v99, 4, v99
	v_add_u32_e32 v101, v150, v99
	v_add_u32_e32 v99, v151, v99
	ds_read_b128 v[154:157], v101
	ds_read_b128 v[158:161], v101 offset:4096
	ds_read_b128 v[162:165], v99 offset:32768
	ds_read_b128 v[166:169], v99 offset:36864
	s_waitcnt lgkmcnt(1)
	v_mfma_f32_32x32x16_bf16 v[50:65], v[154:157], v[162:165], v[50:65]
	v_mfma_f32_32x32x16_bf16 v[18:33], v[158:161], v[162:165], v[18:33]
	s_waitcnt lgkmcnt(0)
	v_mfma_f32_32x32x16_bf16 v[34:49], v[154:157], v[166:169], v[34:49]
	v_mfma_f32_32x32x16_bf16 v[2:17], v[158:161], v[166:169], v[2:17]
	s_add_i32 s22, s22, 2
	s_cmp_lg_u32 s22, 8
	s_cbranch_scc1 .LBB0_441
	s_barrier
	s_waitcnt vmcnt(5)
	ds_write_b128 v144, v[66:69]
	s_waitcnt vmcnt(4)
	ds_write_b128 v145, v[70:73]
	s_waitcnt vmcnt(3)
	ds_write_b128 v146, v[74:77]
	s_waitcnt vmcnt(2)
	ds_write_b128 v147, v[78:81]
	s_waitcnt vmcnt(1)
	ds_write_b128 v144, v[82:85] offset:32768
	s_waitcnt vmcnt(0)
	ds_write_b128 v145, v[86:89] offset:32768
	global_load_dwordx4 v[66:69], v[128:129], off offset:1408
	global_load_dwordx4 v[70:73], v[130:131], off offset:1408
	global_load_dwordx4 v[74:77], v[132:133], off offset:1408
	global_load_dwordx4 v[78:81], v[134:135], off offset:1408
	global_load_dwordx4 v[82:85], v[136:137], off offset:1408
	global_load_dwordx4 v[86:89], v[138:139], off offset:1408
	s_mov_b32 s22, 0
.LBB0_443:
	v_add_u32_e32 v99, s22, v140
	v_xor_b32_e32 v99, v99, v141
	v_lshlrev_b32_e32 v99, 4, v99
	v_add_u32_e32 v101, v150, v99
	v_add_u32_e32 v99, v152, v99
	ds_read_b128 v[154:157], v101 offset:49152
	ds_read_b128 v[158:161], v101 offset:53248
	ds_read_b128 v[162:165], v99 offset:32768
	ds_read_b128 v[166:169], v99 offset:36864
	s_waitcnt lgkmcnt(1)
	v_mfma_f32_32x32x16_bf16 v[50:65], v[154:157], v[162:165], v[50:65]
	v_mfma_f32_32x32x16_bf16 v[18:33], v[158:161], v[162:165], v[18:33]
	s_waitcnt lgkmcnt(0)
	v_mfma_f32_32x32x16_bf16 v[34:49], v[154:157], v[166:169], v[34:49]
	v_mfma_f32_32x32x16_bf16 v[2:17], v[158:161], v[166:169], v[2:17]
	s_add_i32 s22, s22, 2
	s_cmp_lg_u32 s22, 8
	s_cbranch_scc1 .LBB0_443
	s_barrier
	s_waitcnt vmcnt(5)
	ds_write_b128 v144, v[66:69] offset:49152
	s_waitcnt vmcnt(4)
	ds_write_b128 v145, v[70:73] offset:49152
	s_waitcnt vmcnt(3)
	ds_write_b128 v146, v[74:77] offset:49152
	s_waitcnt vmcnt(2)
	ds_write_b128 v147, v[78:81] offset:49152
	s_waitcnt vmcnt(1)
	ds_write_b128 v148, v[82:85]
	s_waitcnt vmcnt(0)
	ds_write_b128 v149, v[86:89]
	global_load_dwordx4 v[66:69], v[128:129], off offset:1536
	global_load_dwordx4 v[70:73], v[130:131], off offset:1536
	global_load_dwordx4 v[74:77], v[132:133], off offset:1536
	global_load_dwordx4 v[78:81], v[134:135], off offset:1536
	global_load_dwordx4 v[82:85], v[136:137], off offset:1536
	global_load_dwordx4 v[86:89], v[138:139], off offset:1536
	s_mov_b32 s22, 0
.LBB0_445:
	v_add_u32_e32 v99, s22, v140
	v_xor_b32_e32 v99, v99, v141
	v_lshlrev_b32_e32 v99, 4, v99
	v_add_u32_e32 v101, v150, v99
	v_add_u32_e32 v99, v151, v99
	ds_read_b128 v[154:157], v101
	ds_read_b128 v[158:161], v101 offset:4096
	ds_read_b128 v[162:165], v99 offset:32768
	ds_read_b128 v[166:169], v99 offset:36864
	s_waitcnt lgkmcnt(1)
	v_mfma_f32_32x32x16_bf16 v[50:65], v[154:157], v[162:165], v[50:65]
	v_mfma_f32_32x32x16_bf16 v[18:33], v[158:161], v[162:165], v[18:33]
	s_waitcnt lgkmcnt(0)
	v_mfma_f32_32x32x16_bf16 v[34:49], v[154:157], v[166:169], v[34:49]
	v_mfma_f32_32x32x16_bf16 v[2:17], v[158:161], v[166:169], v[2:17]
	s_add_i32 s22, s22, 2
	s_cmp_lg_u32 s22, 8
	s_cbranch_scc1 .LBB0_445
	s_barrier
	s_waitcnt vmcnt(5)
	ds_write_b128 v144, v[66:69]
	s_waitcnt vmcnt(4)
	ds_write_b128 v145, v[70:73]
	s_waitcnt vmcnt(3)
	ds_write_b128 v146, v[74:77]
	s_waitcnt vmcnt(2)
	ds_write_b128 v147, v[78:81]
	s_waitcnt vmcnt(1)
	ds_write_b128 v144, v[82:85] offset:32768
	s_waitcnt vmcnt(0)
	ds_write_b128 v145, v[86:89] offset:32768
	global_load_dwordx4 v[66:69], v[128:129], off offset:1664
	global_load_dwordx4 v[70:73], v[130:131], off offset:1664
	global_load_dwordx4 v[74:77], v[132:133], off offset:1664
	global_load_dwordx4 v[78:81], v[134:135], off offset:1664
	global_load_dwordx4 v[82:85], v[136:137], off offset:1664
	global_load_dwordx4 v[86:89], v[138:139], off offset:1664
	s_mov_b32 s22, 0
.LBB0_447:
	v_add_u32_e32 v99, s22, v140
	v_xor_b32_e32 v99, v99, v141
	v_lshlrev_b32_e32 v99, 4, v99
	v_add_u32_e32 v101, v150, v99
	v_add_u32_e32 v99, v152, v99
	ds_read_b128 v[154:157], v101 offset:49152
	ds_read_b128 v[158:161], v101 offset:53248
	ds_read_b128 v[162:165], v99 offset:32768
	ds_read_b128 v[166:169], v99 offset:36864
	s_waitcnt lgkmcnt(1)
	v_mfma_f32_32x32x16_bf16 v[50:65], v[154:157], v[162:165], v[50:65]
	v_mfma_f32_32x32x16_bf16 v[18:33], v[158:161], v[162:165], v[18:33]
	s_waitcnt lgkmcnt(0)
	v_mfma_f32_32x32x16_bf16 v[34:49], v[154:157], v[166:169], v[34:49]
	v_mfma_f32_32x32x16_bf16 v[2:17], v[158:161], v[166:169], v[2:17]
	s_add_i32 s22, s22, 2
	s_cmp_lg_u32 s22, 8
	s_cbranch_scc1 .LBB0_447
	s_barrier
	s_waitcnt vmcnt(5)
	ds_write_b128 v144, v[66:69] offset:49152
	s_waitcnt vmcnt(4)
	ds_write_b128 v145, v[70:73] offset:49152
	s_waitcnt vmcnt(3)
	ds_write_b128 v146, v[74:77] offset:49152
	s_waitcnt vmcnt(2)
	ds_write_b128 v147, v[78:81] offset:49152
	s_waitcnt vmcnt(1)
	ds_write_b128 v148, v[82:85]
	s_waitcnt vmcnt(0)
	ds_write_b128 v149, v[86:89]
	global_load_dwordx4 v[66:69], v[128:129], off offset:1792
	global_load_dwordx4 v[70:73], v[130:131], off offset:1792
	global_load_dwordx4 v[74:77], v[132:133], off offset:1792
	global_load_dwordx4 v[78:81], v[134:135], off offset:1792
	global_load_dwordx4 v[82:85], v[136:137], off offset:1792
	global_load_dwordx4 v[86:89], v[138:139], off offset:1792
	s_mov_b32 s22, 0
.LBB0_449:
	v_add_u32_e32 v99, s22, v140
	v_xor_b32_e32 v99, v99, v141
	v_lshlrev_b32_e32 v99, 4, v99
	v_add_u32_e32 v101, v150, v99
	v_add_u32_e32 v99, v151, v99
	ds_read_b128 v[154:157], v101
	ds_read_b128 v[158:161], v101 offset:4096
	ds_read_b128 v[162:165], v99 offset:32768
	ds_read_b128 v[166:169], v99 offset:36864
	s_waitcnt lgkmcnt(1)
	v_mfma_f32_32x32x16_bf16 v[50:65], v[154:157], v[162:165], v[50:65]
	v_mfma_f32_32x32x16_bf16 v[18:33], v[158:161], v[162:165], v[18:33]
	s_waitcnt lgkmcnt(0)
	v_mfma_f32_32x32x16_bf16 v[34:49], v[154:157], v[166:169], v[34:49]
	v_mfma_f32_32x32x16_bf16 v[2:17], v[158:161], v[166:169], v[2:17]
	s_add_i32 s22, s22, 2
	s_cmp_lg_u32 s22, 8
	s_cbranch_scc1 .LBB0_449
	s_barrier
	s_waitcnt vmcnt(5)
	ds_write_b128 v144, v[66:69]
	s_waitcnt vmcnt(4)
	ds_write_b128 v145, v[70:73]
	s_waitcnt vmcnt(3)
	ds_write_b128 v146, v[74:77]
	s_waitcnt vmcnt(2)
	ds_write_b128 v147, v[78:81]
	s_waitcnt vmcnt(1)
	ds_write_b128 v144, v[82:85] offset:32768
	s_waitcnt vmcnt(0)
	ds_write_b128 v145, v[86:89] offset:32768
	global_load_dwordx4 v[66:69], v[128:129], off offset:1920
	global_load_dwordx4 v[70:73], v[130:131], off offset:1920
	global_load_dwordx4 v[74:77], v[132:133], off offset:1920
	global_load_dwordx4 v[78:81], v[134:135], off offset:1920
	global_load_dwordx4 v[82:85], v[136:137], off offset:1920
	global_load_dwordx4 v[86:89], v[138:139], off offset:1920
	s_mov_b32 s22, 0
.LBB0_451:
	v_add_u32_e32 v99, s22, v140
	v_xor_b32_e32 v99, v99, v141
	v_lshlrev_b32_e32 v99, 4, v99
	v_add_u32_e32 v101, v150, v99
	v_add_u32_e32 v99, v152, v99
	ds_read_b128 v[128:131], v101 offset:49152
	ds_read_b128 v[132:135], v101 offset:53248
	ds_read_b128 v[136:139], v99 offset:32768
	ds_read_b128 v[154:157], v99 offset:36864
	s_waitcnt lgkmcnt(1)
	v_mfma_f32_32x32x16_bf16 v[50:65], v[128:131], v[136:139], v[50:65]
	v_mfma_f32_32x32x16_bf16 v[18:33], v[132:135], v[136:139], v[18:33]
	s_waitcnt lgkmcnt(0)
	v_mfma_f32_32x32x16_bf16 v[34:49], v[128:131], v[154:157], v[34:49]
	v_mfma_f32_32x32x16_bf16 v[2:17], v[132:135], v[154:157], v[2:17]
	s_add_i32 s22, s22, 2
	s_cmp_lg_u32 s22, 8
	s_cbranch_scc1 .LBB0_451
	s_mov_b32 s22, 0
	s_barrier
	s_waitcnt vmcnt(5)
	ds_write_b128 v144, v[66:69] offset:49152
	s_waitcnt vmcnt(4)
	ds_write_b128 v145, v[70:73] offset:49152
	s_waitcnt vmcnt(3)
	ds_write_b128 v146, v[74:77] offset:49152
	s_waitcnt vmcnt(2)
	ds_write_b128 v147, v[78:81] offset:49152
	s_waitcnt vmcnt(1)
	ds_write_b128 v148, v[82:85]
	s_waitcnt vmcnt(0)
	ds_write_b128 v149, v[86:89]
.LBB0_453:
	v_add_u32_e32 v66, s22, v140
	v_xor_b32_e32 v66, v66, v141
	v_lshlrev_b32_e32 v74, 4, v66
	v_add_u32_e32 v70, v150, v74
	v_add_u32_e32 v78, v151, v74
	ds_read_b128 v[66:69], v70
	ds_read_b128 v[70:73], v70 offset:4096
	ds_read_b128 v[74:77], v78 offset:32768
	ds_read_b128 v[78:81], v78 offset:36864
	s_waitcnt lgkmcnt(1)
	v_mfma_f32_32x32x16_bf16 v[50:65], v[66:69], v[74:77], v[50:65]
	v_mfma_f32_32x32x16_bf16 v[18:33], v[70:73], v[74:77], v[18:33]
	s_waitcnt lgkmcnt(0)
	v_mfma_f32_32x32x16_bf16 v[34:49], v[66:69], v[78:81], v[34:49]
	v_mfma_f32_32x32x16_bf16 v[2:17], v[70:73], v[78:81], v[2:17]
	s_add_i32 s22, s22, 2
	s_cmp_lg_u32 s22, 8
	s_cbranch_scc1 .LBB0_453
	s_mov_b32 s22, 0
	s_barrier
.LBB0_455:
	v_add_u32_e32 v66, s22, v140
	v_xor_b32_e32 v66, v66, v141
	v_lshlrev_b32_e32 v74, 4, v66
	v_add_u32_e32 v70, v150, v74
	v_add_u32_e32 v78, v152, v74
	ds_read_b128 v[66:69], v70 offset:49152
	ds_read_b128 v[70:73], v70 offset:53248
	ds_read_b128 v[74:77], v78 offset:32768
	ds_read_b128 v[78:81], v78 offset:36864
	s_waitcnt lgkmcnt(1)
	v_mfma_f32_32x32x16_bf16 v[50:65], v[66:69], v[74:77], v[50:65]
	v_mfma_f32_32x32x16_bf16 v[18:33], v[70:73], v[74:77], v[18:33]
	s_waitcnt lgkmcnt(0)
	v_mfma_f32_32x32x16_bf16 v[34:49], v[66:69], v[78:81], v[34:49]
	v_mfma_f32_32x32x16_bf16 v[2:17], v[70:73], v[78:81], v[2:17]
	s_add_i32 s22, s22, 2
	s_cmp_lg_u32 s22, 8
	s_cbranch_scc1 .LBB0_455
	v_add_u32_e32 v68, s40, v142
	v_add_u32_e32 v66, 0xfffff000, v68
	v_lshrrev_b32_e32 v67, 11, v66
	s_movk_i32 s4, 0x1800
	s_movk_i32 s22, 0xfff
	v_mad_u32_u24 v153, v67, s4, s4
	v_cmp_lt_i32_e32 vcc, s22, v68
	v_ashrrev_i32_e32 v69, 31, v68
	v_readlane_b32 s4, v254, 0
	v_or_b32_e32 v66, s42, v143
	v_cndmask_b32_e32 v158, 0, v153, vcc
	v_lshlrev_b64 v[70:71], 12, v[68:69]
	v_readlane_b32 s5, v254, 1
	v_ashrrev_i32_e32 v67, 31, v66
	s_nop 0
	v_lshl_add_u64 v[72:73], s[4:5], 0, v[70:71]
	v_add_u32_e32 v70, v158, v66
	v_ashrrev_i32_e32 v71, 31, v70
	v_lshl_add_u64 v[70:71], v[70:71], 2, s[28:29]
	s_barrier
	global_load_dword v69, v[70:71], off
	v_lshlrev_b64 v[70:71], 2, v[66:67]
	v_lshl_add_u64 v[74:75], v[72:73], 0, v[70:71]
	v_mov_b32_e32 v111, v1
	v_lshl_add_u64 v[72:73], v[74:75], 0, v[0:1]
	v_mov_b32_e32 v99, v1
	v_mov_b32_e32 v101, v1
	v_mov_b32_e32 v103, v1
	v_mov_b32_e32 v105, v1
	v_mov_b32_e32 v107, v1
	v_mov_b32_e32 v109, v1
	v_lshl_add_u64 v[88:89], v[74:75], 0, v[110:111]
	v_mov_b32_e32 v113, v1
	v_lshl_add_u64 v[76:77], v[74:75], 0, v[98:99]
	v_lshl_add_u64 v[78:79], v[74:75], 0, v[100:101]
	v_lshl_add_u64 v[80:81], v[74:75], 0, v[102:103]
	v_lshl_add_u64 v[82:83], v[74:75], 0, v[104:105]
	v_lshl_add_u64 v[84:85], v[74:75], 0, v[106:107]
	v_lshl_add_u64 v[86:87], v[74:75], 0, v[108:109]
	global_load_dword v67, v[72:73], off
	global_load_dword v159, v[76:77], off
	global_load_dword v160, v[78:79], off
	global_load_dword v161, v[80:81], off
	global_load_dword v162, v[82:83], off
	global_load_dword v163, v[84:85], off
	global_load_dword v164, v[86:87], off
	global_load_dword v165, v[88:89], off
	v_lshl_add_u64 v[128:129], v[74:75], 0, v[112:113]
	v_mov_b32_e32 v115, v1
	global_load_dword v166, v[128:129], off
	v_lshl_add_u64 v[130:131], v[74:75], 0, v[114:115]
	v_mov_b32_e32 v117, v1
	global_load_dword v167, v[130:131], off
	v_lshl_add_u64 v[132:133], v[74:75], 0, v[116:117]
	v_mov_b32_e32 v119, v1
	global_load_dword v168, v[132:133], off
	v_lshl_add_u64 v[134:135], v[74:75], 0, v[118:119]
	v_mov_b32_e32 v121, v1
	global_load_dword v169, v[134:135], off
	v_lshl_add_u64 v[136:137], v[74:75], 0, v[120:121]
	v_mov_b32_e32 v123, v1
	global_load_dword v170, v[136:137], off
	v_lshl_add_u64 v[138:139], v[74:75], 0, v[122:123]
	v_mov_b32_e32 v125, v1
	global_load_dword v171, v[138:139], off
	global_load_dword v175, v[72:73], off offset:128
	v_lshl_add_u64 v[154:155], v[74:75], 0, v[124:125]
	v_mov_b32_e32 v127, v1
	global_load_dword v172, v[154:155], off
	v_lshl_add_u64 v[156:157], v[74:75], 0, v[126:127]
	global_load_dword v173, v[156:157], off
	v_add_f32_e32 v50, 0, v50
	v_readlane_b32 s8, v254, 4
	v_readlane_b32 s9, v254, 5
	v_add_f32_e32 v51, 0, v51
	v_add_f32_e32 v52, 0, v52
	v_add_f32_e32 v53, 0, v53
	v_add_f32_e32 v54, 0, v54
	v_add_f32_e32 v55, 0, v55
	v_add_f32_e32 v56, 0, v56
	v_or_b32_e32 v174, 32, v66
	s_mov_b64 s[8:9], 0x80
	v_add_f32_e32 v34, 0, v34
	v_add_f32_e32 v35, 0, v35
	v_add_f32_e32 v36, 0, v36
	v_add_f32_e32 v37, 0, v37
	v_add_f32_e32 v38, 0, v38
	v_add_f32_e32 v39, 0, v39
	v_add_f32_e32 v40, 0, v40
	v_add_f32_e32 v18, 0, v18
	v_add_f32_e32 v19, 0, v19
	v_add_f32_e32 v20, 0, v20
	v_add_f32_e32 v21, 0, v21
	v_add_f32_e32 v2, 0, v2
	s_add_i32 s1, s1, s0
	v_readlane_b32 s6, v254, 2
	v_readlane_b32 s7, v254, 3
	v_add_f32_e32 v3, 0, v3
	v_add_f32_e32 v4, 0, v4
	s_cmpk_gt_i32 s1, 0xff
	v_readlane_b32 s10, v254, 6
	v_readlane_b32 s11, v254, 7
	v_readlane_b32 s12, v254, 8
	v_readlane_b32 s13, v254, 9
	v_readlane_b32 s14, v254, 10
	v_readlane_b32 s15, v254, 11
	v_readlane_b32 s16, v254, 12
	v_readlane_b32 s17, v254, 13
	v_readlane_b32 s18, v254, 14
	v_readlane_b32 s19, v254, 15
	s_waitcnt vmcnt(16)
	v_fmac_f32_e32 v67, v50, v69
	v_add_f32_e32 v50, 0, v57
	s_waitcnt vmcnt(15)
	v_fmac_f32_e32 v159, v51, v69
	s_waitcnt vmcnt(14)
	v_fmac_f32_e32 v160, v52, v69
	s_waitcnt vmcnt(13)
	v_fmac_f32_e32 v161, v53, v69
	s_waitcnt vmcnt(12)
	v_fmac_f32_e32 v162, v54, v69
	s_waitcnt vmcnt(11)
	v_fmac_f32_e32 v163, v55, v69
	s_waitcnt vmcnt(9)
	v_fmac_f32_e32 v165, v50, v69
	v_add_f32_e32 v50, 0, v58
	v_fmac_f32_e32 v164, v56, v69
	s_waitcnt vmcnt(8)
	v_fmac_f32_e32 v166, v50, v69
	v_add_f32_e32 v50, 0, v59
	global_store_dword v[72:73], v67, off
	global_store_dword v[76:77], v159, off
	global_store_dword v[78:79], v160, off
	global_store_dword v[80:81], v161, off
	global_store_dword v[82:83], v162, off
	global_store_dword v[84:85], v163, off
	global_store_dword v[86:87], v164, off
	s_waitcnt vmcnt(14)
	v_fmac_f32_e32 v167, v50, v69
	v_add_f32_e32 v50, 0, v60
	v_add_f32_e32 v67, 0, v65
	s_waitcnt vmcnt(13)
	v_fmac_f32_e32 v168, v50, v69
	v_add_f32_e32 v50, 0, v61
	global_store_dword v[88:89], v165, off
	s_waitcnt vmcnt(13)
	v_fmac_f32_e32 v169, v50, v69
	v_add_f32_e32 v50, 0, v62
	global_store_dword v[128:129], v166, off
	s_waitcnt vmcnt(13)
	v_fmac_f32_e32 v170, v50, v69
	v_add_f32_e32 v50, 0, v63
	global_store_dword v[130:131], v167, off
	s_waitcnt vmcnt(13)
	v_fmac_f32_e32 v171, v50, v69
	v_add_f32_e32 v50, 0, v64
	global_store_dword v[132:133], v168, off
	global_store_dword v[134:135], v169, off
	s_waitcnt vmcnt(13)
	v_fmac_f32_e32 v172, v50, v69
	v_lshl_add_u64 v[50:51], v[74:75], 0, s[8:9]
	v_add_u32_e32 v74, v158, v174
	global_store_dword v[136:137], v170, off
	global_store_dword v[138:139], v171, off
	global_store_dword v[154:155], v172, off
	v_lshl_add_u64 v[52:53], v[50:51], 0, v[98:99]
	s_waitcnt vmcnt(15)
	v_fmac_f32_e32 v173, v67, v69
	v_ashrrev_i32_e32 v75, 31, v74
	v_lshl_add_u64 v[54:55], v[50:51], 0, v[100:101]
	v_lshl_add_u64 v[56:57], v[50:51], 0, v[102:103]
	v_lshl_add_u64 v[58:59], v[50:51], 0, v[104:105]
	v_lshl_add_u64 v[60:61], v[50:51], 0, v[106:107]
	v_lshl_add_u64 v[62:63], v[50:51], 0, v[108:109]
	v_lshl_add_u64 v[64:65], v[50:51], 0, v[110:111]
	global_load_dword v88, v[52:53], off
	global_load_dword v89, v[54:55], off
	global_load_dword v128, v[56:57], off
	global_load_dword v129, v[58:59], off
	global_load_dword v130, v[60:61], off
	global_load_dword v131, v[62:63], off
	global_load_dword v132, v[64:65], off
	v_lshl_add_u64 v[74:75], v[74:75], 2, s[28:29]
	global_store_dword v[156:157], v173, off
	global_load_dword v67, v[74:75], off
	v_lshl_add_u64 v[74:75], v[50:51], 0, v[112:113]
	global_load_dword v69, v[74:75], off
	v_lshl_add_u64 v[76:77], v[50:51], 0, v[114:115]
	global_load_dword v133, v[76:77], off
	v_lshl_add_u64 v[78:79], v[50:51], 0, v[116:117]
	global_load_dword v134, v[78:79], off
	v_lshl_add_u64 v[80:81], v[50:51], 0, v[118:119]
	global_load_dword v135, v[80:81], off
	v_lshl_add_u64 v[82:83], v[50:51], 0, v[120:121]
	global_load_dword v136, v[82:83], off
	v_lshl_add_u64 v[84:85], v[50:51], 0, v[122:123]
	global_load_dword v137, v[84:85], off
	v_lshl_add_u64 v[86:87], v[50:51], 0, v[124:125]
	global_load_dword v138, v[86:87], off
	v_lshl_add_u64 v[50:51], v[50:51], 0, v[126:127]
	global_load_dword v139, v[50:51], off
	s_waitcnt vmcnt(8)
	v_fmac_f32_e32 v175, v34, v67
	v_add_f32_e32 v34, 0, v41
	v_fmac_f32_e32 v132, v34, v67
	v_add_f32_e32 v34, 0, v42
	s_waitcnt vmcnt(7)
	v_fmac_f32_e32 v69, v34, v67
	v_add_f32_e32 v34, 0, v43
	s_waitcnt vmcnt(6)
	v_fmac_f32_e32 v133, v34, v67
	v_add_f32_e32 v34, 0, v44
	s_waitcnt vmcnt(5)
	v_fmac_f32_e32 v134, v34, v67
	v_add_f32_e32 v34, 0, v45
	s_waitcnt vmcnt(4)
	v_fmac_f32_e32 v135, v34, v67
	v_add_f32_e32 v34, 0, v46
	s_waitcnt vmcnt(3)
	v_fmac_f32_e32 v136, v34, v67
	v_add_f32_e32 v34, 0, v47
	s_waitcnt vmcnt(2)
	v_fmac_f32_e32 v137, v34, v67
	v_add_f32_e32 v34, 0, v48
	s_waitcnt vmcnt(1)
	v_fmac_f32_e32 v138, v34, v67
	v_add_f32_e32 v34, 0, v49
	s_waitcnt vmcnt(0)
	v_fmac_f32_e32 v139, v34, v67
	v_or_b32_e32 v34, 32, v68
	v_cmp_lt_i32_e32 vcc, s22, v34
	v_fmac_f32_e32 v88, v35, v67
	v_ashrrev_i32_e32 v35, 31, v34
	v_cndmask_b32_e32 v68, 0, v153, vcc
	v_fmac_f32_e32 v89, v36, v67
	v_lshlrev_b64 v[34:35], 12, v[34:35]
	v_add_u32_e32 v36, v68, v66
	v_fmac_f32_e32 v128, v37, v67
	v_lshl_add_u64 v[34:35], s[4:5], 0, v[34:35]
	v_ashrrev_i32_e32 v37, 31, v36
	v_fmac_f32_e32 v129, v38, v67
	v_fmac_f32_e32 v130, v39, v67
	v_fmac_f32_e32 v131, v40, v67
	global_store_dword v[72:73], v175, off offset:128
	global_store_dword v[52:53], v88, off
	global_store_dword v[54:55], v89, off
	global_store_dword v[56:57], v128, off
	global_store_dword v[58:59], v129, off
	global_store_dword v[60:61], v130, off
	global_store_dword v[62:63], v131, off
	global_store_dword v[64:65], v132, off
	global_store_dword v[74:75], v69, off
	global_store_dword v[76:77], v133, off
	global_store_dword v[78:79], v134, off
	global_store_dword v[80:81], v135, off
	global_store_dword v[82:83], v136, off
	global_store_dword v[84:85], v137, off
	global_store_dword v[86:87], v138, off
	global_store_dword v[50:51], v139, off
	v_lshl_add_u64 v[36:37], v[36:37], 2, s[28:29]
	v_lshl_add_u64 v[34:35], v[34:35], 0, v[70:71]
	global_load_dword v69, v[36:37], off
	v_lshl_add_u64 v[36:37], v[34:35], 0, v[0:1]
	v_lshl_add_u64 v[42:43], v[34:35], 0, v[102:103]
	v_lshl_add_u64 v[44:45], v[34:35], 0, v[104:105]
	v_lshl_add_u64 v[38:39], v[34:35], 0, v[98:99]
	v_lshl_add_u64 v[40:41], v[34:35], 0, v[100:101]
	global_load_dword v70, v[36:37], off
	global_load_dword v71, v[38:39], off
	global_load_dword v72, v[40:41], off
	global_load_dword v73, v[42:43], off
	global_load_dword v74, v[44:45], off
	v_lshl_add_u64 v[46:47], v[34:35], 0, v[106:107]
	global_load_dword v75, v[46:47], off
	v_lshl_add_u64 v[48:49], v[34:35], 0, v[108:109]
	global_load_dword v76, v[48:49], off
	v_lshl_add_u64 v[50:51], v[34:35], 0, v[110:111]
	global_load_dword v77, v[50:51], off
	v_lshl_add_u64 v[52:53], v[34:35], 0, v[112:113]
	global_load_dword v78, v[52:53], off
	v_lshl_add_u64 v[54:55], v[34:35], 0, v[114:115]
	global_load_dword v79, v[54:55], off
	global_load_dword v86, v[36:37], off offset:128
	v_lshl_add_u64 v[56:57], v[34:35], 0, v[116:117]
	global_load_dword v80, v[56:57], off
	v_lshl_add_u64 v[58:59], v[34:35], 0, v[118:119]
	global_load_dword v81, v[58:59], off
	v_lshl_add_u64 v[60:61], v[34:35], 0, v[120:121]
	global_load_dword v82, v[60:61], off
	v_lshl_add_u64 v[62:63], v[34:35], 0, v[122:123]
	global_load_dword v83, v[62:63], off
	v_lshl_add_u64 v[64:65], v[34:35], 0, v[124:125]
	global_load_dword v84, v[64:65], off
	v_lshl_add_u64 v[66:67], v[34:35], 0, v[126:127]
	global_load_dword v85, v[66:67], off
	s_waitcnt vmcnt(16)
	v_fmac_f32_e32 v70, v18, v69
	v_add_f32_e32 v18, 0, v22
	s_waitcnt vmcnt(15)
	v_fmac_f32_e32 v71, v19, v69
	s_waitcnt vmcnt(14)
	v_fmac_f32_e32 v72, v20, v69
	s_waitcnt vmcnt(12)
	v_fmac_f32_e32 v74, v18, v69
	v_add_f32_e32 v18, 0, v23
	s_waitcnt vmcnt(11)
	v_fmac_f32_e32 v75, v18, v69
	v_add_f32_e32 v18, 0, v24
	s_waitcnt vmcnt(10)
	v_fmac_f32_e32 v76, v18, v69
	v_add_f32_e32 v18, 0, v25
	s_waitcnt vmcnt(9)
	v_fmac_f32_e32 v77, v18, v69
	v_add_f32_e32 v18, 0, v26
	s_waitcnt vmcnt(8)
	v_fmac_f32_e32 v78, v18, v69
	v_add_f32_e32 v18, 0, v27
	s_waitcnt vmcnt(7)
	v_fmac_f32_e32 v79, v18, v69
	v_add_f32_e32 v18, 0, v28
	global_store_dword v[36:37], v70, off
	global_store_dword v[38:39], v71, off
	global_store_dword v[40:41], v72, off
	s_waitcnt vmcnt(8)
	v_fmac_f32_e32 v80, v18, v69
	v_add_f32_e32 v18, 0, v29
	s_waitcnt vmcnt(7)
	v_fmac_f32_e32 v81, v18, v69
	v_add_f32_e32 v18, 0, v30
	s_waitcnt vmcnt(6)
	v_fmac_f32_e32 v82, v18, v69
	v_add_f32_e32 v18, 0, v31
	s_waitcnt vmcnt(5)
	v_fmac_f32_e32 v83, v18, v69
	v_add_f32_e32 v18, 0, v32
	v_fmac_f32_e32 v73, v21, v69
	s_waitcnt vmcnt(4)
	v_fmac_f32_e32 v84, v18, v69
	v_add_f32_e32 v38, 0, v33
	v_lshl_add_u64 v[18:19], v[34:35], 0, s[8:9]
	v_add_u32_e32 v34, v68, v174
	global_store_dword v[42:43], v73, off
	global_store_dword v[44:45], v74, off
	global_store_dword v[46:47], v75, off
	global_store_dword v[48:49], v76, off
	global_store_dword v[50:51], v77, off
	global_store_dword v[52:53], v78, off
	global_store_dword v[54:55], v79, off
	global_store_dword v[56:57], v80, off
	global_store_dword v[58:59], v81, off
	global_store_dword v[60:61], v82, off
	global_store_dword v[62:63], v83, off
	global_store_dword v[64:65], v84, off
	v_lshl_add_u64 v[20:21], v[18:19], 0, v[98:99]
	s_waitcnt vmcnt(15)
	v_fmac_f32_e32 v85, v38, v69
	v_ashrrev_i32_e32 v35, 31, v34
	v_lshl_add_u64 v[22:23], v[18:19], 0, v[100:101]
	v_lshl_add_u64 v[24:25], v[18:19], 0, v[102:103]
	v_lshl_add_u64 v[26:27], v[18:19], 0, v[104:105]
	v_lshl_add_u64 v[28:29], v[18:19], 0, v[106:107]
	v_lshl_add_u64 v[30:31], v[18:19], 0, v[108:109]
	v_lshl_add_u64 v[32:33], v[18:19], 0, v[110:111]
	global_load_dword v50, v[20:21], off
	global_load_dword v51, v[22:23], off
	global_load_dword v52, v[24:25], off
	global_load_dword v53, v[26:27], off
	global_load_dword v54, v[28:29], off
	global_load_dword v55, v[30:31], off
	global_load_dword v56, v[32:33], off
	v_lshl_add_u64 v[34:35], v[34:35], 2, s[28:29]
	global_store_dword v[66:67], v85, off
	global_load_dword v57, v[34:35], off
	v_lshl_add_u64 v[34:35], v[18:19], 0, v[112:113]
	global_load_dword v58, v[34:35], off
	v_lshl_add_u64 v[38:39], v[18:19], 0, v[114:115]
	global_load_dword v59, v[38:39], off
	v_lshl_add_u64 v[40:41], v[18:19], 0, v[116:117]
	global_load_dword v60, v[40:41], off
	v_lshl_add_u64 v[42:43], v[18:19], 0, v[118:119]
	global_load_dword v61, v[42:43], off
	v_lshl_add_u64 v[44:45], v[18:19], 0, v[120:121]
	global_load_dword v62, v[44:45], off
	v_lshl_add_u64 v[46:47], v[18:19], 0, v[122:123]
	global_load_dword v63, v[46:47], off
	v_lshl_add_u64 v[48:49], v[18:19], 0, v[124:125]
	global_load_dword v64, v[48:49], off
	v_lshl_add_u64 v[18:19], v[18:19], 0, v[126:127]
	global_load_dword v65, v[18:19], off
	s_waitcnt vmcnt(8)
	v_fmac_f32_e32 v86, v2, v57
	v_add_f32_e32 v2, 0, v5
	v_fmac_f32_e32 v52, v2, v57
	v_add_f32_e32 v2, 0, v6
	v_fmac_f32_e32 v53, v2, v57
	v_add_f32_e32 v2, 0, v7
	v_fmac_f32_e32 v54, v2, v57
	v_add_f32_e32 v2, 0, v8
	v_fmac_f32_e32 v55, v2, v57
	v_add_f32_e32 v2, 0, v9
	v_fmac_f32_e32 v56, v2, v57
	v_add_f32_e32 v2, 0, v10
	s_waitcnt vmcnt(7)
	v_fmac_f32_e32 v58, v2, v57
	v_add_f32_e32 v2, 0, v11
	s_waitcnt vmcnt(6)
	v_fmac_f32_e32 v59, v2, v57
	v_add_f32_e32 v2, 0, v12
	s_waitcnt vmcnt(5)
	v_fmac_f32_e32 v60, v2, v57
	v_add_f32_e32 v2, 0, v13
	s_waitcnt vmcnt(4)
	v_fmac_f32_e32 v61, v2, v57
	v_add_f32_e32 v2, 0, v14
	s_waitcnt vmcnt(3)
	v_fmac_f32_e32 v62, v2, v57
	v_add_f32_e32 v2, 0, v15
	s_waitcnt vmcnt(2)
	v_fmac_f32_e32 v63, v2, v57
	v_add_f32_e32 v2, 0, v16
	s_waitcnt vmcnt(1)
	v_fmac_f32_e32 v64, v2, v57
	v_add_f32_e32 v2, 0, v17
	s_waitcnt vmcnt(0)
	v_fmac_f32_e32 v65, v2, v57
	v_fmac_f32_e32 v50, v3, v57
	v_fmac_f32_e32 v51, v4, v57
	global_store_dword v[36:37], v86, off offset:128
	global_store_dword v[20:21], v50, off
	global_store_dword v[22:23], v51, off
	global_store_dword v[24:25], v52, off
	global_store_dword v[26:27], v53, off
	global_store_dword v[28:29], v54, off
	global_store_dword v[30:31], v55, off
	global_store_dword v[32:33], v56, off
	global_store_dword v[34:35], v58, off
	global_store_dword v[38:39], v59, off
	global_store_dword v[40:41], v60, off
	global_store_dword v[42:43], v61, off
	global_store_dword v[44:45], v62, off
	global_store_dword v[46:47], v63, off
	global_store_dword v[48:49], v64, off
	global_store_dword v[18:19], v65, off
	s_cbranch_scc0 .LBB0_424

.LBB0_696:
	v_add_u32_e32 v3, s22, v113
	v_xor_b32_e32 v3, v3, v114
	v_lshlrev_b32_e32 v3, 4, v3
	v_add_u32_e32 v8, v0, v3
	v_add_u32_e32 v3, v2, v3
	ds_read_b128 v[4:7], v8
	ds_read_b128 v[8:11], v8 offset:4096
	ds_read_b128 v[12:15], v3 offset:32768
	ds_read_b128 v[128:131], v3 offset:36864
	s_waitcnt lgkmcnt(1)
	v_mfma_f32_32x32x16_bf16 v[48:63], v[4:7], v[12:15], v[48:63]
	v_mfma_f32_32x32x16_bf16 v[16:31], v[8:11], v[12:15], v[16:31]
	s_waitcnt lgkmcnt(0)
	v_mfma_f32_32x32x16_bf16 v[64:79], v[4:7], v[128:131], v[64:79]
	v_mfma_f32_32x32x16_bf16 v[32:47], v[8:11], v[128:131], v[32:47]
	s_add_i32 s22, s22, 2
	s_cmp_eq_u32 s22, 8
	s_cbranch_scc0 .LBB0_696
	s_cmp_eq_u32 s21, s1
	s_barrier
	s_cbranch_scc0 .LBB0_693
	v_add_u32_e32 v6, 0x800, v126
	s_nop 2
	ds_write2_b32 v126, v48, v64 offset1:32
	ds_write2_b32 v126, v49, v65 offset0:65 offset1:97
	ds_write2_b32 v126, v50, v66 offset0:130 offset1:162
	ds_write2_b32 v126, v51, v67 offset0:195 offset1:227
	ds_write2_b32 v6, v52, v68 offset0:8 offset1:40
	ds_write2_b32 v6, v53, v69 offset0:73 offset1:105
	ds_write2_b32 v6, v54, v70 offset0:138 offset1:170
	ds_write2_b32 v6, v55, v71 offset0:203 offset1:235
	v_add_u32_e32 v6, 0x1000, v126
	ds_write2_b32 v6, v56, v72 offset0:16 offset1:48
	ds_write2_b32 v6, v57, v73 offset0:81 offset1:113
	ds_write2_b32 v6, v58, v74 offset0:146 offset1:178
	ds_write2_b32 v6, v59, v75 offset0:211 offset1:243
	v_add_u32_e32 v6, 0x1800, v126
	ds_write2_b32 v6, v60, v76 offset0:24 offset1:56
	ds_write2_b32 v6, v61, v77 offset0:89 offset1:121
	ds_write2_b32 v6, v62, v78 offset0:154 offset1:186
	ds_write2_b32 v6, v63, v79 offset0:219 offset1:251
	v_add_u32_e32 v6, 0x2000, v126
	ds_write2_b32 v6, v16, v32 offset0:32 offset1:64
	ds_write2_b32 v6, v17, v33 offset0:97 offset1:129
	ds_write2_b32 v6, v18, v34 offset0:162 offset1:194
	v_add_u32_e32 v6, 0x2200, v126
	ds_write2_b32 v6, v19, v35 offset0:99 offset1:131
	v_add_u32_e32 v6, 0x2800, v126
	ds_write2_b32 v6, v20, v36 offset0:40 offset1:72
	ds_write2_b32 v6, v21, v37 offset0:105 offset1:137
	ds_write2_b32 v6, v22, v38 offset0:170 offset1:202
	v_add_u32_e32 v6, 0x2a00, v126
	ds_write2_b32 v6, v23, v39 offset0:107 offset1:139
	v_add_u32_e32 v6, 0x3000, v126
	v_add_u32_e32 v4, s20, v115
	ds_write2_b32 v6, v24, v40 offset0:48 offset1:80
	ds_write2_b32 v6, v25, v41 offset0:113 offset1:145
	ds_write2_b32 v6, v26, v42 offset0:178 offset1:210
	v_add_u32_e32 v6, 0x3200, v126
	v_or_b32_e32 v2, s0, v116
	s_movk_i32 s1, 0x3ff
	v_ashrrev_i32_e32 v5, 31, v4
	ds_write2_b32 v6, v27, v43 offset0:115 offset1:147
	v_add_u32_e32 v6, 0x3800, v126
	v_or_b32_e32 v0, v2, v112
	v_cmp_lt_i32_e32 vcc, s1, v2
	v_lshlrev_b64 v[2:3], 12, v[4:5]
	ds_write2_b32 v6, v28, v44 offset0:56 offset1:88
	ds_write2_b32 v6, v29, v45 offset0:121 offset1:153
	ds_write2_b32 v6, v30, v46 offset0:186 offset1:218
	v_add_u32_e32 v6, 0x3a00, v126
	ds_write2_b32 v6, v31, v47 offset0:123 offset1:155
	s_waitcnt lgkmcnt(0)
	s_barrier
	s_and_saveexec_b64 s[20:21], vcc
	s_xor_b64 s[40:41], exec, s[20:21]
	s_cbranch_execz .LBB0_706
	s_cmpk_gt_u32 s0, 0x7ff
	s_mov_b64 s[0:1], -1
	s_cbranch_scc0 .LBB0_703
	v_readlane_b32 s4, v253, 36
	v_lshlrev_b64 v[4:5], 10, v[4:5]
	v_readlane_b32 s5, v253, 37
	s_mov_b32 s20, 1
	s_mov_b32 s21, 0
	v_lshl_add_u64 v[4:5], s[4:5], 0, v[4:5]
	v_lshl_add_u64 v[4:5], v[0:1], 1, v[4:5]
	s_mov_b32 s22, 64
	v_readlane_b32 s6, v253, 38
	v_readlane_b32 s7, v253, 39
	v_readlane_b32 s8, v253, 40
	v_readlane_b32 s9, v253, 41
	v_readlane_b32 s10, v253, 42
	v_readlane_b32 s11, v253, 43

.LBB0_866:
	v_add_u32_e32 v3, s21, v105
	v_xor_b32_e32 v3, v3, v122
	v_lshlrev_b32_e32 v3, 4, v3
	v_add_u32_e32 v8, v0, v3
	v_add_u32_e32 v3, v2, v3
	ds_read_b128 v[4:7], v8
	ds_read_b128 v[8:11], v8 offset:4096
	ds_read_b128 v[12:15], v3 offset:32768
	ds_read_b128 v[142:145], v3 offset:36864
	s_waitcnt lgkmcnt(1)
	v_mfma_f32_32x32x16_bf16 v[32:47], v[4:7], v[12:15], v[32:47]
	v_mfma_f32_32x32x16_bf16 v[16:31], v[8:11], v[12:15], v[16:31]
	s_waitcnt lgkmcnt(0)
	v_mfma_f32_32x32x16_bf16 v[48:63], v[4:7], v[142:145], v[48:63]
	v_mfma_f32_32x32x16_bf16 v[64:79], v[8:11], v[142:145], v[64:79]
	s_add_i32 s21, s21, 2
	s_cmp_eq_u32 s21, 8
	s_cbranch_scc0 .LBB0_866
	s_cmp_eq_u32 s1, 16
	s_barrier
	s_cbranch_scc0 .LBB0_862
	v_add_u32_e32 v2, s20, v123
	s_movk_i32 s1, 0x1000
	v_cmp_gt_i32_e64 s[42:43], s1, v2
	v_add_u32_e32 v3, 0xfffff000, v2
	s_movk_i32 s1, 0xfff
	v_lshrrev_b32_e32 v3, 11, v3
	v_ashrrev_i32_e32 v10, 8, v2
	v_cmp_lt_i32_e64 s[44:45], s1, v2
	ds_write2_b32 v141, v32, v48 offset1:32
	ds_write2_b32 v141, v33, v49 offset0:65 offset1:97
	ds_write2_b32 v141, v34, v50 offset0:130 offset1:162
	ds_write2_b32 v141, v35, v51 offset0:195 offset1:227
	v_cndmask_b32_e64 v9, v10, v3, s[44:45]
	v_and_b32_e32 v3, 0x7c0, v2
	v_cndmask_b32_e64 v8, v127, v3, s[44:45]
	v_add_u32_e32 v3, 0x800, v141
	ds_write2_b32 v3, v36, v52 offset0:8 offset1:40
	ds_write2_b32 v3, v37, v53 offset0:73 offset1:105
	ds_write2_b32 v3, v38, v54 offset0:138 offset1:170
	ds_write2_b32 v3, v39, v55 offset0:203 offset1:235
	v_add_u32_e32 v3, 0x1000, v141
	ds_write2_b32 v3, v40, v56 offset0:16 offset1:48
	ds_write2_b32 v3, v41, v57 offset0:81 offset1:113
	ds_write2_b32 v3, v42, v58 offset0:146 offset1:178
	ds_write2_b32 v3, v43, v59 offset0:211 offset1:243
	v_add_u32_e32 v3, 0x1800, v141
	ds_write2_b32 v3, v44, v60 offset0:24 offset1:56
	ds_write2_b32 v3, v45, v61 offset0:89 offset1:121
	ds_write2_b32 v3, v46, v62 offset0:154 offset1:186
	ds_write2_b32 v3, v47, v63 offset0:219 offset1:251
	v_add_u32_e32 v3, 0x2000, v141
	ds_write2_b32 v3, v16, v64 offset0:32 offset1:64
	ds_write2_b32 v3, v17, v65 offset0:97 offset1:129
	ds_write2_b32 v3, v18, v66 offset0:162 offset1:194
	v_add_u32_e32 v3, 0x2200, v141
	ds_write2_b32 v3, v19, v67 offset0:99 offset1:131
	v_add_u32_e32 v3, 0x2800, v141
	ds_write2_b32 v3, v20, v68 offset0:40 offset1:72
	ds_write2_b32 v3, v21, v69 offset0:105 offset1:137
	ds_write2_b32 v3, v22, v70 offset0:170 offset1:202
	v_add_u32_e32 v3, 0x2a00, v141
	ds_write2_b32 v3, v23, v71 offset0:107 offset1:139
	v_add_u32_e32 v3, 0x3000, v141
	ds_write2_b32 v3, v24, v72 offset0:48 offset1:80
	ds_write2_b32 v3, v25, v73 offset0:113 offset1:145
	ds_write2_b32 v3, v26, v74 offset0:178 offset1:210
	v_add_u32_e32 v3, 0x3200, v141
	v_or_b32_e32 v0, s0, v124
	s_movk_i32 s1, 0x3ff
	ds_write2_b32 v3, v27, v75 offset0:115 offset1:147
	v_add_u32_e32 v3, 0x3800, v141
	v_cmp_lt_i32_e32 vcc, s1, v0
	ds_write2_b32 v3, v28, v76 offset0:56 offset1:88
	ds_write2_b32 v3, v29, v77 offset0:121 offset1:153
	ds_write2_b32 v3, v30, v78 offset0:186 offset1:218
	v_add_u32_e32 v3, 0x3a00, v141
	ds_write2_b32 v3, v31, v79 offset0:123 offset1:155
	s_waitcnt lgkmcnt(0)
	s_barrier
	s_and_saveexec_b64 s[20:21], vcc
	s_xor_b64 s[28:29], exec, s[20:21]
	s_cbranch_execz .LBB0_880
	s_cmpk_gt_u32 s0, 0x5ff
	s_mov_b64 s[0:1], -1
	s_cbranch_scc0 .LBB0_873
	v_readlane_b32 s4, v253, 46
	v_readlane_b32 s12, v253, 54
	v_readlane_b32 s13, v253, 55
	s_movk_i32 s0, 0x1c00
	s_mov_b32 s20, 1
	v_mov_b64_e32 v[4:5], s[12:13]
	v_mad_i64_i32 v[2:3], s[0:1], v2, s0, v[4:5]
	v_lshl_add_u64 v[2:3], v[0:1], 2, v[2:3]
	v_lshlrev_b32_e32 v4, 2, v104
	v_mov_b32_e32 v5, v1
	s_movk_i32 s0, 0xe800
	v_lshl_add_u64 v[2:3], v[2:3], 0, v[4:5]
	s_mov_b32 s1, -1
	v_lshl_add_u64 v[2:3], v[2:3], 0, s[0:1]
	s_mov_b32 s21, 0
	s_mov_b32 s22, 64
	v_readlane_b32 s5, v253, 47
	v_readlane_b32 s6, v253, 48
	v_readlane_b32 s7, v253, 49
	v_readlane_b32 s8, v253, 50
	v_readlane_b32 s9, v253, 51
	v_readlane_b32 s10, v253, 52
	v_readlane_b32 s11, v253, 53
	v_readlane_b32 s14, v253, 56
	v_readlane_b32 s15, v253, 57
	v_readlane_b32 s16, v253, 58
	v_readlane_b32 s17, v253, 59
	v_readlane_b32 s18, v253, 60
	v_readlane_b32 s19, v253, 61

.Lw13_loop:
	s_waitcnt vmcnt(0)
	s_barrier
	ds_read_b128 v[4:7], v172
	ds_read_b128 v[8:11], v172 offset:4096
	ds_read_b128 v[12:15], v192 offset:32768
	ds_read_b128 v[246:249], v192 offset:36864
	ds_read_b128 v[214:217], v192 offset:40960
	ds_read_b128 v[218:221], v192 offset:45056
	ds_read_b128 v[144:147], v173
	ds_read_b128 v[148:151], v173 offset:4096
	ds_read_b128 v[152:155], v193 offset:32768
	ds_read_b128 v[156:159], v193 offset:36864
	ds_read_b128 v[160:163], v193 offset:40960
	ds_read_b128 v[164:167], v193 offset:45056
	s_waitcnt lgkmcnt(6)
	v_mfma_f32_32x32x16_bf16 v[112:127], v[4:7], v[12:15], v[112:127]
	s_mov_b32 m0, s43
	v_mfma_f32_32x32x16_bf16 v[80:95], v[8:11], v[12:15], v[80:95]
	global_load_lds_dwordx4 v168, s[22:23]
	s_add_u32 m0, m0, 0x2000
	v_mfma_f32_32x32x16_bf16 v[128:143], v[4:7], v[246:249], v[128:143]
	global_load_lds_dwordx4 v169, s[22:23]
	s_add_u32 m0, m0, 0x2000
	v_mfma_f32_32x32x16_bf16 v[96:111], v[8:11], v[246:249], v[96:111]
	global_load_lds_dwordx4 v170, s[22:23]
	s_add_u32 m0, m0, 0x2000
	v_mfma_f32_32x32x16_bf16 v[64:79], v[4:7], v[214:217], v[64:79]
	global_load_lds_dwordx4 v171, s[22:23]
	s_add_u32 m0, m0, 0x2000
	v_mfma_f32_32x32x16_bf16 v[16:31], v[8:11], v[214:217], v[16:31]
	global_load_lds_dwordx4 v168, s[24:25]
	s_add_u32 m0, m0, 0x2000
	v_mfma_f32_32x32x16_bf16 v[48:63], v[4:7], v[218:221], v[48:63]
	global_load_lds_dwordx4 v169, s[24:25]
	s_add_u32 m0, m0, 0x2000
	v_mfma_f32_32x32x16_bf16 v[32:47], v[8:11], v[218:221], v[32:47]
	global_load_lds_dwordx4 v170, s[24:25]
	s_add_u32 m0, m0, 0x2000
	s_nop 0
	global_load_lds_dwordx4 v171, s[24:25]
	s_add_u32 s22, s22, 0x80
	s_addc_u32 s23, s23, 0
	s_add_u32 s24, s24, 0x80
	s_addc_u32 s25, s25, 0
	ds_read_b128 v[4:7], v174
	ds_read_b128 v[8:11], v174 offset:4096
	ds_read_b128 v[12:15], v194 offset:32768
	ds_read_b128 v[246:249], v194 offset:36864
	ds_read_b128 v[214:217], v194 offset:40960
	ds_read_b128 v[218:221], v194 offset:45056
	s_waitcnt lgkmcnt(6)
	v_mfma_f32_32x32x16_bf16 v[112:127], v[144:147], v[152:155], v[112:127]
	v_mfma_f32_32x32x16_bf16 v[80:95], v[148:151], v[152:155], v[80:95]
	v_mfma_f32_32x32x16_bf16 v[128:143], v[144:147], v[156:159], v[128:143]
	v_mfma_f32_32x32x16_bf16 v[96:111], v[148:151], v[156:159], v[96:111]
	v_mfma_f32_32x32x16_bf16 v[64:79], v[144:147], v[160:163], v[64:79]
	v_mfma_f32_32x32x16_bf16 v[16:31], v[148:151], v[160:163], v[16:31]
	v_mfma_f32_32x32x16_bf16 v[48:63], v[144:147], v[164:167], v[48:63]
	v_mfma_f32_32x32x16_bf16 v[32:47], v[148:151], v[164:167], v[32:47]
	ds_read_b128 v[144:147], v175
	ds_read_b128 v[148:151], v175 offset:4096
	ds_read_b128 v[152:155], v195 offset:32768
	ds_read_b128 v[156:159], v195 offset:36864
	ds_read_b128 v[160:163], v195 offset:40960
	ds_read_b128 v[164:167], v195 offset:45056
	s_waitcnt lgkmcnt(6)
	v_mfma_f32_32x32x16_bf16 v[112:127], v[4:7], v[12:15], v[112:127]
	v_mfma_f32_32x32x16_bf16 v[80:95], v[8:11], v[12:15], v[80:95]
	v_mfma_f32_32x32x16_bf16 v[128:143], v[4:7], v[246:249], v[128:143]
	v_mfma_f32_32x32x16_bf16 v[96:111], v[8:11], v[246:249], v[96:111]
	v_mfma_f32_32x32x16_bf16 v[64:79], v[4:7], v[214:217], v[64:79]
	v_mfma_f32_32x32x16_bf16 v[16:31], v[8:11], v[214:217], v[16:31]
	v_mfma_f32_32x32x16_bf16 v[48:63], v[4:7], v[218:221], v[48:63]
	v_mfma_f32_32x32x16_bf16 v[32:47], v[8:11], v[218:221], v[32:47]
	s_waitcnt lgkmcnt(0)
	v_mfma_f32_32x32x16_bf16 v[112:127], v[144:147], v[152:155], v[112:127]
	v_mfma_f32_32x32x16_bf16 v[80:95], v[148:151], v[152:155], v[80:95]
	v_mfma_f32_32x32x16_bf16 v[128:143], v[144:147], v[156:159], v[128:143]
	v_mfma_f32_32x32x16_bf16 v[96:111], v[148:151], v[156:159], v[96:111]
	v_mfma_f32_32x32x16_bf16 v[64:79], v[144:147], v[160:163], v[64:79]
	v_mfma_f32_32x32x16_bf16 v[16:31], v[148:151], v[160:163], v[16:31]
	v_mfma_f32_32x32x16_bf16 v[48:63], v[144:147], v[164:167], v[48:63]
	v_mfma_f32_32x32x16_bf16 v[32:47], v[148:151], v[164:167], v[32:47]
	s_cmp_eq_u32 s1, 1
	s_cbranch_scc1 .Lw13_last
	s_waitcnt vmcnt(0)
	s_barrier
	ds_read_b128 v[4:7], v188
	ds_read_b128 v[8:11], v188 offset:4096
	ds_read_b128 v[12:15], v237 offset:32768
	ds_read_b128 v[246:249], v237 offset:36864
	ds_read_b128 v[214:217], v237 offset:40960
	ds_read_b128 v[218:221], v237 offset:45056
	ds_read_b128 v[144:147], v189
	ds_read_b128 v[148:151], v189 offset:4096
	ds_read_b128 v[152:155], v238 offset:32768
	ds_read_b128 v[156:159], v238 offset:36864
	ds_read_b128 v[160:163], v238 offset:40960
	ds_read_b128 v[164:167], v238 offset:45056
	s_waitcnt lgkmcnt(6)
	v_mfma_f32_32x32x16_bf16 v[112:127], v[4:7], v[12:15], v[112:127]
	s_mov_b32 m0, s42
	v_mfma_f32_32x32x16_bf16 v[80:95], v[8:11], v[12:15], v[80:95]
	global_load_lds_dwordx4 v168, s[22:23]
	s_add_u32 m0, m0, 0x2000
	v_mfma_f32_32x32x16_bf16 v[128:143], v[4:7], v[246:249], v[128:143]
	global_load_lds_dwordx4 v169, s[22:23]
	s_add_u32 m0, m0, 0x2000
	v_mfma_f32_32x32x16_bf16 v[96:111], v[8:11], v[246:249], v[96:111]
	global_load_lds_dwordx4 v170, s[22:23]
	s_add_u32 m0, m0, 0x2000
	v_mfma_f32_32x32x16_bf16 v[64:79], v[4:7], v[214:217], v[64:79]
	global_load_lds_dwordx4 v171, s[22:23]
	s_add_u32 m0, m0, 0x2000
	v_mfma_f32_32x32x16_bf16 v[16:31], v[8:11], v[214:217], v[16:31]
	global_load_lds_dwordx4 v168, s[24:25]
	s_add_u32 m0, m0, 0x2000
	v_mfma_f32_32x32x16_bf16 v[48:63], v[4:7], v[218:221], v[48:63]
	global_load_lds_dwordx4 v169, s[24:25]
	s_add_u32 m0, m0, 0x2000
	v_mfma_f32_32x32x16_bf16 v[32:47], v[8:11], v[218:221], v[32:47]
	global_load_lds_dwordx4 v170, s[24:25]
	s_add_u32 m0, m0, 0x2000
	s_nop 0
	global_load_lds_dwordx4 v171, s[24:25]
	s_add_u32 s22, s22, 0x80
	s_addc_u32 s23, s23, 0
	s_add_u32 s24, s24, 0x80
	s_addc_u32 s25, s25, 0
	ds_read_b128 v[4:7], v190
	ds_read_b128 v[8:11], v190 offset:4096
	ds_read_b128 v[12:15], v239 offset:32768
	ds_read_b128 v[246:249], v239 offset:36864
	ds_read_b128 v[214:217], v239 offset:40960
	ds_read_b128 v[218:221], v239 offset:45056
	s_waitcnt lgkmcnt(6)
	v_mfma_f32_32x32x16_bf16 v[112:127], v[144:147], v[152:155], v[112:127]
	v_mfma_f32_32x32x16_bf16 v[80:95], v[148:151], v[152:155], v[80:95]
	v_mfma_f32_32x32x16_bf16 v[128:143], v[144:147], v[156:159], v[128:143]
	v_mfma_f32_32x32x16_bf16 v[96:111], v[148:151], v[156:159], v[96:111]
	v_mfma_f32_32x32x16_bf16 v[64:79], v[144:147], v[160:163], v[64:79]
	v_mfma_f32_32x32x16_bf16 v[16:31], v[148:151], v[160:163], v[16:31]
	v_mfma_f32_32x32x16_bf16 v[48:63], v[144:147], v[164:167], v[48:63]
	v_mfma_f32_32x32x16_bf16 v[32:47], v[148:151], v[164:167], v[32:47]
	ds_read_b128 v[144:147], v191
	ds_read_b128 v[148:151], v191 offset:4096
	ds_read_b128 v[152:155], v240 offset:32768
	ds_read_b128 v[156:159], v240 offset:36864
	ds_read_b128 v[160:163], v240 offset:40960
	ds_read_b128 v[164:167], v240 offset:45056
	s_waitcnt lgkmcnt(6)
	v_mfma_f32_32x32x16_bf16 v[112:127], v[4:7], v[12:15], v[112:127]
	v_mfma_f32_32x32x16_bf16 v[80:95], v[8:11], v[12:15], v[80:95]
	v_mfma_f32_32x32x16_bf16 v[128:143], v[4:7], v[246:249], v[128:143]
	v_mfma_f32_32x32x16_bf16 v[96:111], v[8:11], v[246:249], v[96:111]
	v_mfma_f32_32x32x16_bf16 v[64:79], v[4:7], v[214:217], v[64:79]
	v_mfma_f32_32x32x16_bf16 v[16:31], v[8:11], v[214:217], v[16:31]
	v_mfma_f32_32x32x16_bf16 v[48:63], v[4:7], v[218:221], v[48:63]
	v_mfma_f32_32x32x16_bf16 v[32:47], v[8:11], v[218:221], v[32:47]
	s_waitcnt lgkmcnt(0)
	v_mfma_f32_32x32x16_bf16 v[112:127], v[144:147], v[152:155], v[112:127]
	v_mfma_f32_32x32x16_bf16 v[80:95], v[148:151], v[152:155], v[80:95]
	v_mfma_f32_32x32x16_bf16 v[128:143], v[144:147], v[156:159], v[128:143]
	v_mfma_f32_32x32x16_bf16 v[96:111], v[148:151], v[156:159], v[96:111]
	v_mfma_f32_32x32x16_bf16 v[64:79], v[144:147], v[160:163], v[64:79]
	v_mfma_f32_32x32x16_bf16 v[16:31], v[148:151], v[160:163], v[16:31]
	v_mfma_f32_32x32x16_bf16 v[48:63], v[144:147], v[164:167], v[48:63]
	v_mfma_f32_32x32x16_bf16 v[32:47], v[148:151], v[164:167], v[32:47]
	s_add_i32 s1, s1, -1
	s_branch .Lw13_loop
.Lw13_last:
	s_waitcnt vmcnt(0)
	s_barrier
	ds_read_b128 v[4:7], v188
	ds_read_b128 v[8:11], v188 offset:4096
	ds_read_b128 v[12:15], v237 offset:32768
	ds_read_b128 v[246:249], v237 offset:36864
	ds_read_b128 v[214:217], v237 offset:40960
	ds_read_b128 v[218:221], v237 offset:45056
	ds_read_b128 v[144:147], v189
	ds_read_b128 v[148:151], v189 offset:4096
	ds_read_b128 v[152:155], v238 offset:32768
	ds_read_b128 v[156:159], v238 offset:36864
	ds_read_b128 v[160:163], v238 offset:40960
	ds_read_b128 v[164:167], v238 offset:45056
	s_waitcnt lgkmcnt(6)
	v_mfma_f32_32x32x16_bf16 v[112:127], v[4:7], v[12:15], v[112:127]
	v_mfma_f32_32x32x16_bf16 v[80:95], v[8:11], v[12:15], v[80:95]
	v_mfma_f32_32x32x16_bf16 v[128:143], v[4:7], v[246:249], v[128:143]
	v_mfma_f32_32x32x16_bf16 v[96:111], v[8:11], v[246:249], v[96:111]
	v_mfma_f32_32x32x16_bf16 v[64:79], v[4:7], v[214:217], v[64:79]
	v_mfma_f32_32x32x16_bf16 v[16:31], v[8:11], v[214:217], v[16:31]
	v_mfma_f32_32x32x16_bf16 v[48:63], v[4:7], v[218:221], v[48:63]
	v_mfma_f32_32x32x16_bf16 v[32:47], v[8:11], v[218:221], v[32:47]
	ds_read_b128 v[4:7], v190
	ds_read_b128 v[8:11], v190 offset:4096
	ds_read_b128 v[12:15], v239 offset:32768
	ds_read_b128 v[246:249], v239 offset:36864
	ds_read_b128 v[214:217], v239 offset:40960
	ds_read_b128 v[218:221], v239 offset:45056
	s_waitcnt lgkmcnt(6)
	v_mfma_f32_32x32x16_bf16 v[112:127], v[144:147], v[152:155], v[112:127]
	v_mfma_f32_32x32x16_bf16 v[80:95], v[148:151], v[152:155], v[80:95]
	v_mfma_f32_32x32x16_bf16 v[128:143], v[144:147], v[156:159], v[128:143]
	v_mfma_f32_32x32x16_bf16 v[96:111], v[148:151], v[156:159], v[96:111]
	v_mfma_f32_32x32x16_bf16 v[64:79], v[144:147], v[160:163], v[64:79]
	v_mfma_f32_32x32x16_bf16 v[16:31], v[148:151], v[160:163], v[16:31]
	v_mfma_f32_32x32x16_bf16 v[48:63], v[144:147], v[164:167], v[48:63]
	v_mfma_f32_32x32x16_bf16 v[32:47], v[148:151], v[164:167], v[32:47]
	ds_read_b128 v[144:147], v191
	ds_read_b128 v[148:151], v191 offset:4096
	ds_read_b128 v[152:155], v240 offset:32768
	ds_read_b128 v[156:159], v240 offset:36864
	ds_read_b128 v[160:163], v240 offset:40960
	ds_read_b128 v[164:167], v240 offset:45056
	s_waitcnt lgkmcnt(6)
	v_mfma_f32_32x32x16_bf16 v[112:127], v[4:7], v[12:15], v[112:127]
	v_mfma_f32_32x32x16_bf16 v[80:95], v[8:11], v[12:15], v[80:95]
	v_mfma_f32_32x32x16_bf16 v[128:143], v[4:7], v[246:249], v[128:143]
	v_mfma_f32_32x32x16_bf16 v[96:111], v[8:11], v[246:249], v[96:111]
	v_mfma_f32_32x32x16_bf16 v[64:79], v[4:7], v[214:217], v[64:79]
	v_mfma_f32_32x32x16_bf16 v[16:31], v[8:11], v[214:217], v[16:31]
	v_mfma_f32_32x32x16_bf16 v[48:63], v[4:7], v[218:221], v[48:63]
	v_mfma_f32_32x32x16_bf16 v[32:47], v[8:11], v[218:221], v[32:47]
	s_waitcnt lgkmcnt(0)
	v_mfma_f32_32x32x16_bf16 v[112:127], v[144:147], v[152:155], v[112:127]
	v_mfma_f32_32x32x16_bf16 v[80:95], v[148:151], v[152:155], v[80:95]
	v_mfma_f32_32x32x16_bf16 v[128:143], v[144:147], v[156:159], v[128:143]
	v_mfma_f32_32x32x16_bf16 v[96:111], v[148:151], v[156:159], v[96:111]
	v_mfma_f32_32x32x16_bf16 v[64:79], v[144:147], v[160:163], v[64:79]
	v_mfma_f32_32x32x16_bf16 v[16:31], v[148:151], v[160:163], v[16:31]
	v_mfma_f32_32x32x16_bf16 v[48:63], v[144:147], v[164:167], v[48:63]
	v_mfma_f32_32x32x16_bf16 v[32:47], v[148:151], v[164:167], v[32:47]
	s_mov_b32 s44, 0
	s_add_i32 s1, s30, s27
	s_cmpk_gt_i32 s1, 0x2bf
	s_cbranch_scc1 .Lw13_nopf
	s_and_b32 s21, s1, 31
	s_lshl_b32 s21, s21, 19
	s_add_u32 s22, s6, s21
	s_addc_u32 s23, s7, 0
	s_lshr_b32 s21, s1, 5
	s_lshl_b32 s21, s21, 19
	s_add_u32 s24, s40, s21
	s_addc_u32 s25, s41, 0
	s_mov_b32 m0, s42
	s_nop 0
	global_load_lds_dwordx4 v168, s[22:23]
	s_add_u32 m0, m0, 0x2000
	s_nop 0
	global_load_lds_dwordx4 v169, s[22:23]
	s_add_u32 m0, m0, 0x2000
	s_nop 0
	global_load_lds_dwordx4 v170, s[22:23]
	s_add_u32 m0, m0, 0x2000
	s_nop 0
	global_load_lds_dwordx4 v171, s[22:23]
	s_add_u32 m0, m0, 0x2000
	s_nop 0
	global_load_lds_dwordx4 v168, s[24:25]
	s_add_u32 m0, m0, 0x2000
	s_nop 0
	global_load_lds_dwordx4 v169, s[24:25]
	s_add_u32 m0, m0, 0x2000
	s_nop 0
	global_load_lds_dwordx4 v170, s[24:25]
	s_add_u32 m0, m0, 0x2000
	s_nop 0
	global_load_lds_dwordx4 v171, s[24:25]
	s_add_u32 s22, s22, 0x80
	s_addc_u32 s23, s23, 0
	s_add_u32 s24, s24, 0x80
	s_addc_u32 s25, s25, 0
	s_mov_b32 s44, 1

.Lw2_loop:
	s_waitcnt vmcnt(6)
	s_barrier
	s_add_i32 vcc_hi, s41, 2
	s_cmp_ge_u32 vcc_hi, 3
	s_cselect_b32 vcc_lo, 3, 0
	s_sub_i32 vcc_hi, vcc_hi, vcc_lo
	s_mul_i32 vcc_hi, vcc_hi, 0xc000
	s_add_i32 vcc_hi, vcc_hi, s43
	ds_read_b128 v[144:147], v86
	ds_read_b128 v[148:151], v86 offset:4096
	ds_read_b128 v[152:155], v136 offset:32768
	ds_read_b128 v[156:159], v136 offset:36864
	ds_read_b128 v[66:69], v87
	ds_read_b128 v[70:73], v87 offset:4096
	ds_read_b128 v[74:77], v137 offset:32768
	ds_read_b128 v[78:81], v137 offset:36864
	s_waitcnt lgkmcnt(4)
	v_mfma_f32_32x32x16_bf16 v[50:65], v[144:147], v[152:155], v[50:65]
	s_mov_b32 m0, vcc_hi
	v_mfma_f32_32x32x16_bf16 v[18:33], v[148:151], v[152:155], v[18:33]
	global_load_lds_dwordx4 v82, s[0:1]
	s_add_u32 m0, m0, 0x2000
	v_mfma_f32_32x32x16_bf16 v[34:49], v[144:147], v[156:159], v[34:49]
	global_load_lds_dwordx4 v83, s[0:1]
	s_add_u32 m0, m0, 0x2000
	v_mfma_f32_32x32x16_bf16 v[2:17], v[148:151], v[156:159], v[2:17]
	global_load_lds_dwordx4 v84, s[0:1]
	s_add_u32 m0, m0, 0x2000
	s_nop 0
	global_load_lds_dwordx4 v85, s[0:1]
	s_add_u32 m0, m0, 0x2000
	s_nop 0
	global_load_lds_dwordx4 v82, s[20:21]
	s_add_u32 m0, m0, 0x2000
	s_nop 0
	global_load_lds_dwordx4 v83, s[20:21]
	s_add_u32 s0, s0, 0x80
	s_addc_u32 s1, s1, 0
	s_add_u32 s20, s20, 0x80
	s_addc_u32 s21, s21, 0
	ds_read_b128 v[144:147], v88
	ds_read_b128 v[148:151], v88 offset:4096
	ds_read_b128 v[152:155], v138 offset:32768
	ds_read_b128 v[156:159], v138 offset:36864
	s_waitcnt lgkmcnt(4)
	v_mfma_f32_32x32x16_bf16 v[50:65], v[66:69], v[74:77], v[50:65]
	v_mfma_f32_32x32x16_bf16 v[18:33], v[70:73], v[74:77], v[18:33]
	v_mfma_f32_32x32x16_bf16 v[34:49], v[66:69], v[78:81], v[34:49]
	v_mfma_f32_32x32x16_bf16 v[2:17], v[70:73], v[78:81], v[2:17]
	ds_read_b128 v[66:69], v89
	ds_read_b128 v[70:73], v89 offset:4096
	ds_read_b128 v[74:77], v139 offset:32768
	ds_read_b128 v[78:81], v139 offset:36864
	s_waitcnt lgkmcnt(4)
	v_mfma_f32_32x32x16_bf16 v[50:65], v[144:147], v[152:155], v[50:65]
	v_mfma_f32_32x32x16_bf16 v[18:33], v[148:151], v[152:155], v[18:33]
	v_mfma_f32_32x32x16_bf16 v[34:49], v[144:147], v[156:159], v[34:49]
	v_mfma_f32_32x32x16_bf16 v[2:17], v[148:151], v[156:159], v[2:17]
	s_waitcnt lgkmcnt(0)
	v_mfma_f32_32x32x16_bf16 v[50:65], v[66:69], v[74:77], v[50:65]
	v_mfma_f32_32x32x16_bf16 v[18:33], v[70:73], v[74:77], v[18:33]
	v_mfma_f32_32x32x16_bf16 v[34:49], v[66:69], v[78:81], v[34:49]
	v_mfma_f32_32x32x16_bf16 v[2:17], v[70:73], v[78:81], v[2:17]
	s_add_i32 s41, s41, 1
	s_cmp_eq_u32 s41, 3
	s_cselect_b32 vcc_lo, 0xfffdc000, 0
	s_cselect_b32 s41, 0, s41
	s_add_i32 vcc_lo, vcc_lo, 0xc000
	v_add_u32_e32 v86, vcc_lo, v86
	v_add_u32_e32 v136, vcc_lo, v136
	v_add_u32_e32 v87, vcc_lo, v87
	v_add_u32_e32 v137, vcc_lo, v137
	v_add_u32_e32 v88, vcc_lo, v88
	v_add_u32_e32 v138, vcc_lo, v138
	v_add_u32_e32 v89, vcc_lo, v89
	v_add_u32_e32 v139, vcc_lo, v139
	s_add_i32 s40, s40, -1
	s_cmp_lg_u32 s40, 0
	s_cbranch_scc1 .Lw2_loop
	s_waitcnt vmcnt(6)
	s_barrier
	ds_read_b128 v[144:147], v86
	ds_read_b128 v[148:151], v86 offset:4096
	ds_read_b128 v[152:155], v136 offset:32768
	ds_read_b128 v[156:159], v136 offset:36864
	ds_read_b128 v[66:69], v87
	ds_read_b128 v[70:73], v87 offset:4096
	ds_read_b128 v[74:77], v137 offset:32768
	ds_read_b128 v[78:81], v137 offset:36864
	s_waitcnt lgkmcnt(4)
	v_mfma_f32_32x32x16_bf16 v[50:65], v[144:147], v[152:155], v[50:65]
	v_mfma_f32_32x32x16_bf16 v[18:33], v[148:151], v[152:155], v[18:33]
	v_mfma_f32_32x32x16_bf16 v[34:49], v[144:147], v[156:159], v[34:49]
	v_mfma_f32_32x32x16_bf16 v[2:17], v[148:151], v[156:159], v[2:17]
	ds_read_b128 v[144:147], v88
	ds_read_b128 v[148:151], v88 offset:4096
	ds_read_b128 v[152:155], v138 offset:32768
	ds_read_b128 v[156:159], v138 offset:36864
	s_waitcnt lgkmcnt(4)
	v_mfma_f32_32x32x16_bf16 v[50:65], v[66:69], v[74:77], v[50:65]
	v_mfma_f32_32x32x16_bf16 v[18:33], v[70:73], v[74:77], v[18:33]
	v_mfma_f32_32x32x16_bf16 v[34:49], v[66:69], v[78:81], v[34:49]
	v_mfma_f32_32x32x16_bf16 v[2:17], v[70:73], v[78:81], v[2:17]
	ds_read_b128 v[66:69], v89
	ds_read_b128 v[70:73], v89 offset:4096
	ds_read_b128 v[74:77], v139 offset:32768
	ds_read_b128 v[78:81], v139 offset:36864
	s_waitcnt lgkmcnt(4)
	v_mfma_f32_32x32x16_bf16 v[50:65], v[144:147], v[152:155], v[50:65]
	v_mfma_f32_32x32x16_bf16 v[18:33], v[148:151], v[152:155], v[18:33]
	v_mfma_f32_32x32x16_bf16 v[34:49], v[144:147], v[156:159], v[34:49]
	v_mfma_f32_32x32x16_bf16 v[2:17], v[148:151], v[156:159], v[2:17]
	s_waitcnt lgkmcnt(0)
	v_mfma_f32_32x32x16_bf16 v[50:65], v[66:69], v[74:77], v[50:65]
	v_mfma_f32_32x32x16_bf16 v[18:33], v[70:73], v[74:77], v[18:33]
	v_mfma_f32_32x32x16_bf16 v[34:49], v[66:69], v[78:81], v[34:49]
	v_mfma_f32_32x32x16_bf16 v[2:17], v[70:73], v[78:81], v[2:17]
	s_add_i32 s41, s41, 1
	s_cmp_eq_u32 s41, 3
	s_cselect_b32 vcc_lo, 0xfffdc000, 0
	s_cselect_b32 s41, 0, s41
	s_add_i32 vcc_lo, vcc_lo, 0xc000
	v_add_u32_e32 v86, vcc_lo, v86
	v_add_u32_e32 v136, vcc_lo, v136
	v_add_u32_e32 v87, vcc_lo, v87
	v_add_u32_e32 v137, vcc_lo, v137
	v_add_u32_e32 v88, vcc_lo, v88
	v_add_u32_e32 v138, vcc_lo, v138
	v_add_u32_e32 v89, vcc_lo, v89
	v_add_u32_e32 v139, vcc_lo, v139
	s_waitcnt vmcnt(0)
	s_barrier
	ds_read_b128 v[144:147], v86
	ds_read_b128 v[148:151], v86 offset:4096
	ds_read_b128 v[152:155], v136 offset:32768
	ds_read_b128 v[156:159], v136 offset:36864
	ds_read_b128 v[66:69], v87
	ds_read_b128 v[70:73], v87 offset:4096
	ds_read_b128 v[74:77], v137 offset:32768
	ds_read_b128 v[78:81], v137 offset:36864
	s_waitcnt lgkmcnt(4)
	v_mfma_f32_32x32x16_bf16 v[50:65], v[144:147], v[152:155], v[50:65]
	v_mfma_f32_32x32x16_bf16 v[18:33], v[148:151], v[152:155], v[18:33]
	v_mfma_f32_32x32x16_bf16 v[34:49], v[144:147], v[156:159], v[34:49]
	v_mfma_f32_32x32x16_bf16 v[2:17], v[148:151], v[156:159], v[2:17]
	ds_read_b128 v[144:147], v88
	ds_read_b128 v[148:151], v88 offset:4096
	ds_read_b128 v[152:155], v138 offset:32768
	ds_read_b128 v[156:159], v138 offset:36864
	s_waitcnt lgkmcnt(4)
	v_mfma_f32_32x32x16_bf16 v[50:65], v[66:69], v[74:77], v[50:65]
	v_mfma_f32_32x32x16_bf16 v[18:33], v[70:73], v[74:77], v[18:33]
	v_mfma_f32_32x32x16_bf16 v[34:49], v[66:69], v[78:81], v[34:49]
	v_mfma_f32_32x32x16_bf16 v[2:17], v[70:73], v[78:81], v[2:17]
	ds_read_b128 v[66:69], v89
	ds_read_b128 v[70:73], v89 offset:4096
	ds_read_b128 v[74:77], v139 offset:32768
	ds_read_b128 v[78:81], v139 offset:36864
	s_waitcnt lgkmcnt(4)
	v_mfma_f32_32x32x16_bf16 v[50:65], v[144:147], v[152:155], v[50:65]
	v_mfma_f32_32x32x16_bf16 v[18:33], v[148:151], v[152:155], v[18:33]
	v_mfma_f32_32x32x16_bf16 v[34:49], v[144:147], v[156:159], v[34:49]
	v_mfma_f32_32x32x16_bf16 v[2:17], v[148:151], v[156:159], v[2:17]
	s_waitcnt lgkmcnt(0)
	v_mfma_f32_32x32x16_bf16 v[50:65], v[66:69], v[74:77], v[50:65]
	v_mfma_f32_32x32x16_bf16 v[18:33], v[70:73], v[74:77], v[18:33]
	v_mfma_f32_32x32x16_bf16 v[34:49], v[66:69], v[78:81], v[34:49]
	v_mfma_f32_32x32x16_bf16 v[2:17], v[70:73], v[78:81], v[2:17]
	s_barrier
	v_mov_b32_e32 v0, v1
	s_nop 7
	s_waitcnt vmcnt(5)
	v_lshl_add_u32 v68, s26, 8, v132
	v_add_u32_e32 v0, 0xfffff000, v68
	v_lshrrev_b32_e32 v0, 11, v0
	s_movk_i32 s0, 0x1800
	v_mad_u32_u24 v0, v0, s0, s0
	v_cmp_lt_i32_e32 vcc, s50, v68
	v_ashrrev_i32_e32 v69, 31, v68
	v_readlane_b32 s4, v254, 0
	v_or_b32_e32 v66, s27, v135
	v_cndmask_b32_e32 v160, 0, v0, vcc
	s_waitcnt vmcnt(4)
	v_lshlrev_b64 v[70:71], 12, v[68:69]
	v_readlane_b32 s5, v254, 1
	v_ashrrev_i32_e32 v67, 31, v66
	v_mov_b32_e32 v95, v1
	v_lshl_add_u64 v[72:73], s[4:5], 0, v[70:71]
	v_add_u32_e32 v70, v160, v66
	v_ashrrev_i32_e32 v71, 31, v70
	v_lshl_add_u64 v[70:71], v[70:71], 2, s[28:29]
	global_load_dword v69, v[70:71], off
	v_lshlrev_b64 v[70:71], 2, v[66:67]
	s_waitcnt vmcnt(4)
	v_lshl_add_u64 v[74:75], v[72:73], 0, v[70:71]
	v_mov_b32_e32 v109, v1
	v_mov_b32_e32 v111, v1
	v_lshl_add_u64 v[72:73], v[74:75], 0, v[94:95]
	v_mov_b32_e32 v97, v1
	v_mov_b32_e32 v99, v1
	v_mov_b32_e32 v101, v1
	v_mov_b32_e32 v103, v1
	v_mov_b32_e32 v105, v1
	v_mov_b32_e32 v107, v1
	s_waitcnt vmcnt(1)
	v_lshl_add_u64 v[88:89], v[74:75], 0, v[108:109]
	v_lshl_add_u64 v[144:145], v[74:75], 0, v[110:111]
	v_mov_b32_e32 v113, v1
	v_lshl_add_u64 v[76:77], v[74:75], 0, v[96:97]
	v_lshl_add_u64 v[78:79], v[74:75], 0, v[98:99]
	v_lshl_add_u64 v[80:81], v[74:75], 0, v[100:101]
	v_lshl_add_u64 v[82:83], v[74:75], 0, v[102:103]
	v_lshl_add_u64 v[84:85], v[74:75], 0, v[104:105]
	v_lshl_add_u64 v[86:87], v[74:75], 0, v[106:107]
	global_load_dword v67, v[72:73], off
	global_load_dword v161, v[76:77], off
	global_load_dword v162, v[78:79], off
	global_load_dword v163, v[80:81], off
	global_load_dword v164, v[82:83], off
	global_load_dword v165, v[84:85], off
	global_load_dword v166, v[86:87], off
	global_load_dword v167, v[88:89], off
	global_load_dword v168, v[144:145], off
	v_lshl_add_u64 v[146:147], v[74:75], 0, v[112:113]
	v_mov_b32_e32 v115, v1
	global_load_dword v169, v[146:147], off
	v_lshl_add_u64 v[148:149], v[74:75], 0, v[114:115]
	v_mov_b32_e32 v117, v1
	global_load_dword v170, v[148:149], off
	v_lshl_add_u64 v[150:151], v[74:75], 0, v[116:117]
	v_mov_b32_e32 v119, v1
	global_load_dword v171, v[150:151], off
	v_lshl_add_u64 v[152:153], v[74:75], 0, v[118:119]
	v_mov_b32_e32 v121, v1
	global_load_dword v172, v[152:153], off
	v_lshl_add_u64 v[154:155], v[74:75], 0, v[120:121]
	v_mov_b32_e32 v123, v1
	global_load_dword v173, v[154:155], off
	global_load_dword v177, v[72:73], off offset:128
	v_lshl_add_u64 v[156:157], v[74:75], 0, v[122:123]
	v_mov_b32_e32 v125, v1
	global_load_dword v174, v[156:157], off
	v_lshl_add_u64 v[158:159], v[74:75], 0, v[124:125]
	global_load_dword v175, v[158:159], off
	v_add_f32_e32 v50, 0, v50
	v_add_f32_e32 v51, 0, v51
	v_add_f32_e32 v52, 0, v52
	v_add_f32_e32 v53, 0, v53
	v_add_f32_e32 v54, 0, v54
	v_add_f32_e32 v55, 0, v55
	v_add_f32_e32 v56, 0, v56
	v_add_f32_e32 v57, 0, v57
	v_or_b32_e32 v176, 32, v66
	s_mov_b64 s[0:1], 0x80
	v_add_f32_e32 v34, 0, v34
	v_add_f32_e32 v35, 0, v35
	v_add_f32_e32 v36, 0, v36
	v_add_f32_e32 v37, 0, v37
	v_add_f32_e32 v41, 0, v41
	v_add_f32_e32 v38, 0, v38
	v_add_f32_e32 v39, 0, v39
	v_add_f32_e32 v40, 0, v40
	v_add_f32_e32 v18, 0, v18
	v_add_f32_e32 v19, 0, v19
	v_add_f32_e32 v20, 0, v20
	v_add_f32_e32 v21, 0, v21
	v_add_f32_e32 v2, 0, v2
	s_add_i32 s23, s23, s22
	v_add_f32_e32 v3, 0, v3
	v_add_f32_e32 v4, 0, v4
	v_add_f32_e32 v5, 0, v5
	s_cmpk_gt_i32 s23, 0xff
	v_readlane_b32 s6, v254, 2
	v_readlane_b32 s7, v254, 3
	v_readlane_b32 s8, v254, 4
	v_readlane_b32 s9, v254, 5
	v_readlane_b32 s10, v254, 6
	v_readlane_b32 s11, v254, 7
	v_readlane_b32 s12, v254, 8
	v_readlane_b32 s13, v254, 9
	v_readlane_b32 s14, v254, 10
	v_readlane_b32 s15, v254, 11
	v_readlane_b32 s16, v254, 12
	v_readlane_b32 s17, v254, 13
	v_readlane_b32 s18, v254, 14
	v_readlane_b32 s19, v254, 15
	s_waitcnt vmcnt(16)
	v_fmac_f32_e32 v67, v50, v69
	v_add_f32_e32 v50, 0, v58
	s_waitcnt vmcnt(15)
	v_fmac_f32_e32 v161, v51, v69
	s_waitcnt vmcnt(14)
	v_fmac_f32_e32 v162, v52, v69
	s_waitcnt vmcnt(13)
	v_fmac_f32_e32 v163, v53, v69
	s_waitcnt vmcnt(12)
	v_fmac_f32_e32 v164, v54, v69
	s_waitcnt vmcnt(11)
	v_fmac_f32_e32 v165, v55, v69
	s_waitcnt vmcnt(10)
	v_fmac_f32_e32 v166, v56, v69
	s_waitcnt vmcnt(8)
	v_fmac_f32_e32 v168, v50, v69
	v_add_f32_e32 v50, 0, v59
	v_fmac_f32_e32 v167, v57, v69
	s_waitcnt vmcnt(7)
	v_fmac_f32_e32 v169, v50, v69
	v_add_f32_e32 v50, 0, v60
	global_store_dword v[72:73], v67, off
	global_store_dword v[76:77], v161, off
	global_store_dword v[78:79], v162, off
	global_store_dword v[80:81], v163, off
	global_store_dword v[82:83], v164, off
	global_store_dword v[84:85], v165, off
	global_store_dword v[86:87], v166, off
	global_store_dword v[88:89], v167, off
	s_waitcnt vmcnt(14)
	v_fmac_f32_e32 v170, v50, v69
	v_add_f32_e32 v50, 0, v61
	v_add_f32_e32 v67, 0, v65
	s_waitcnt vmcnt(13)
	v_fmac_f32_e32 v171, v50, v69
	v_add_f32_e32 v50, 0, v62
	global_store_dword v[144:145], v168, off
	s_waitcnt vmcnt(13)
	v_fmac_f32_e32 v172, v50, v69
	v_add_f32_e32 v50, 0, v63
	global_store_dword v[146:147], v169, off
	s_waitcnt vmcnt(13)
	v_fmac_f32_e32 v173, v50, v69
	v_add_f32_e32 v50, 0, v64
	global_store_dword v[148:149], v170, off
	global_store_dword v[150:151], v171, off
	s_waitcnt vmcnt(13)
	v_fmac_f32_e32 v174, v50, v69
	v_lshl_add_u64 v[50:51], v[74:75], 0, s[0:1]
	v_add_u32_e32 v74, v160, v176
	global_store_dword v[152:153], v172, off
	global_store_dword v[154:155], v173, off
	global_store_dword v[156:157], v174, off
	v_lshl_add_u64 v[52:53], v[50:51], 0, v[96:97]
	s_waitcnt vmcnt(15)
	v_fmac_f32_e32 v175, v67, v69
	v_ashrrev_i32_e32 v75, 31, v74
	v_lshl_add_u64 v[54:55], v[50:51], 0, v[98:99]
	v_lshl_add_u64 v[56:57], v[50:51], 0, v[100:101]
	v_lshl_add_u64 v[58:59], v[50:51], 0, v[102:103]
	v_lshl_add_u64 v[60:61], v[50:51], 0, v[104:105]
	v_lshl_add_u64 v[62:63], v[50:51], 0, v[106:107]
	v_lshl_add_u64 v[64:65], v[50:51], 0, v[108:109]
	global_load_dword v88, v[52:53], off
	global_load_dword v89, v[54:55], off
	global_load_dword v144, v[56:57], off
	global_load_dword v145, v[58:59], off
	global_load_dword v146, v[60:61], off
	global_load_dword v147, v[62:63], off
	global_load_dword v148, v[64:65], off
	v_lshl_add_u64 v[74:75], v[74:75], 2, s[28:29]
	global_store_dword v[158:159], v175, off
	global_load_dword v67, v[74:75], off
	v_lshl_add_u64 v[74:75], v[50:51], 0, v[110:111]
	global_load_dword v69, v[74:75], off
	v_lshl_add_u64 v[76:77], v[50:51], 0, v[112:113]
	global_load_dword v149, v[76:77], off
	v_lshl_add_u64 v[78:79], v[50:51], 0, v[114:115]
	global_load_dword v150, v[78:79], off
	v_lshl_add_u64 v[80:81], v[50:51], 0, v[116:117]
	global_load_dword v151, v[80:81], off
	v_lshl_add_u64 v[82:83], v[50:51], 0, v[118:119]
	global_load_dword v152, v[82:83], off
	v_lshl_add_u64 v[84:85], v[50:51], 0, v[120:121]
	global_load_dword v153, v[84:85], off
	v_lshl_add_u64 v[86:87], v[50:51], 0, v[122:123]
	global_load_dword v154, v[86:87], off
	v_lshl_add_u64 v[50:51], v[50:51], 0, v[124:125]
	global_load_dword v155, v[50:51], off
	s_waitcnt vmcnt(8)
	v_fmac_f32_e32 v177, v34, v67
	v_add_f32_e32 v34, 0, v42
	s_waitcnt vmcnt(7)
	v_fmac_f32_e32 v69, v34, v67
	v_add_f32_e32 v34, 0, v43
	s_waitcnt vmcnt(6)
	v_fmac_f32_e32 v149, v34, v67
	v_add_f32_e32 v34, 0, v44
	s_waitcnt vmcnt(5)
	v_fmac_f32_e32 v150, v34, v67
	v_add_f32_e32 v34, 0, v45
	s_waitcnt vmcnt(4)
	v_fmac_f32_e32 v151, v34, v67
	v_add_f32_e32 v34, 0, v46
	s_waitcnt vmcnt(3)
	v_fmac_f32_e32 v152, v34, v67
	v_add_f32_e32 v34, 0, v47
	s_waitcnt vmcnt(2)
	v_fmac_f32_e32 v153, v34, v67
	v_add_f32_e32 v34, 0, v48
	s_waitcnt vmcnt(1)
	v_fmac_f32_e32 v154, v34, v67
	v_add_f32_e32 v34, 0, v49
	s_waitcnt vmcnt(0)
	v_fmac_f32_e32 v155, v34, v67
	v_or_b32_e32 v34, 32, v68
	v_cmp_lt_i32_e32 vcc, s50, v34
	v_fmac_f32_e32 v88, v35, v67
	v_ashrrev_i32_e32 v35, 31, v34
	v_cndmask_b32_e32 v0, 0, v0, vcc
	v_fmac_f32_e32 v89, v36, v67
	v_lshlrev_b64 v[34:35], 12, v[34:35]
	v_add_u32_e32 v36, v0, v66
	v_fmac_f32_e32 v144, v37, v67
	v_fmac_f32_e32 v148, v41, v67
	v_lshl_add_u64 v[34:35], s[4:5], 0, v[34:35]
	v_ashrrev_i32_e32 v37, 31, v36
	v_fmac_f32_e32 v145, v38, v67
	v_fmac_f32_e32 v146, v39, v67
	v_fmac_f32_e32 v147, v40, v67
	global_store_dword v[72:73], v177, off offset:128
	global_store_dword v[52:53], v88, off
	global_store_dword v[54:55], v89, off
	global_store_dword v[56:57], v144, off
	global_store_dword v[58:59], v145, off
	global_store_dword v[60:61], v146, off
	global_store_dword v[62:63], v147, off
	global_store_dword v[64:65], v148, off
	global_store_dword v[74:75], v69, off
	global_store_dword v[76:77], v149, off
	global_store_dword v[78:79], v150, off
	global_store_dword v[80:81], v151, off
	global_store_dword v[82:83], v152, off
	global_store_dword v[84:85], v153, off
	global_store_dword v[86:87], v154, off
	global_store_dword v[50:51], v155, off
	v_lshl_add_u64 v[36:37], v[36:37], 2, s[28:29]
	v_lshl_add_u64 v[34:35], v[34:35], 0, v[70:71]
	global_load_dword v68, v[36:37], off
	v_lshl_add_u64 v[36:37], v[34:35], 0, v[94:95]
	v_lshl_add_u64 v[44:45], v[34:35], 0, v[102:103]
	v_lshl_add_u64 v[38:39], v[34:35], 0, v[96:97]
	v_lshl_add_u64 v[40:41], v[34:35], 0, v[98:99]
	v_lshl_add_u64 v[42:43], v[34:35], 0, v[100:101]
	global_load_dword v69, v[36:37], off
	global_load_dword v70, v[38:39], off
	global_load_dword v71, v[40:41], off
	global_load_dword v72, v[42:43], off
	global_load_dword v73, v[44:45], off
	v_lshl_add_u64 v[46:47], v[34:35], 0, v[104:105]
	global_load_dword v74, v[46:47], off
	v_lshl_add_u64 v[48:49], v[34:35], 0, v[106:107]
	global_load_dword v75, v[48:49], off
	v_lshl_add_u64 v[50:51], v[34:35], 0, v[108:109]
	global_load_dword v76, v[50:51], off
	v_lshl_add_u64 v[52:53], v[34:35], 0, v[110:111]
	global_load_dword v77, v[52:53], off
	v_lshl_add_u64 v[54:55], v[34:35], 0, v[112:113]
	global_load_dword v78, v[54:55], off
	v_lshl_add_u64 v[56:57], v[34:35], 0, v[114:115]
	global_load_dword v79, v[56:57], off
	global_load_dword v85, v[36:37], off offset:128
	v_lshl_add_u64 v[58:59], v[34:35], 0, v[116:117]
	global_load_dword v80, v[58:59], off
	v_lshl_add_u64 v[60:61], v[34:35], 0, v[118:119]
	global_load_dword v81, v[60:61], off
	v_lshl_add_u64 v[62:63], v[34:35], 0, v[120:121]
	global_load_dword v82, v[62:63], off
	v_lshl_add_u64 v[64:65], v[34:35], 0, v[122:123]
	global_load_dword v83, v[64:65], off
	v_lshl_add_u64 v[66:67], v[34:35], 0, v[124:125]
	global_load_dword v84, v[66:67], off
	s_waitcnt vmcnt(16)
	v_fmac_f32_e32 v69, v18, v68
	v_add_f32_e32 v18, 0, v22
	s_waitcnt vmcnt(15)
	v_fmac_f32_e32 v70, v19, v68
	s_waitcnt vmcnt(14)
	v_fmac_f32_e32 v71, v20, v68
	s_waitcnt vmcnt(12)
	v_fmac_f32_e32 v73, v18, v68
	v_add_f32_e32 v18, 0, v23
	s_waitcnt vmcnt(11)
	v_fmac_f32_e32 v74, v18, v68
	v_add_f32_e32 v18, 0, v24
	s_waitcnt vmcnt(10)
	v_fmac_f32_e32 v75, v18, v68
	v_add_f32_e32 v18, 0, v25
	s_waitcnt vmcnt(9)
	v_fmac_f32_e32 v76, v18, v68
	v_add_f32_e32 v18, 0, v26
	s_waitcnt vmcnt(8)
	v_fmac_f32_e32 v77, v18, v68
	v_add_f32_e32 v18, 0, v27
	s_waitcnt vmcnt(7)
	v_fmac_f32_e32 v78, v18, v68
	v_add_f32_e32 v18, 0, v28
	s_waitcnt vmcnt(6)
	v_fmac_f32_e32 v79, v18, v68
	v_add_f32_e32 v18, 0, v29
	v_fmac_f32_e32 v72, v21, v68
	s_waitcnt vmcnt(4)
	v_fmac_f32_e32 v80, v18, v68
	v_add_f32_e32 v18, 0, v30
	s_waitcnt vmcnt(3)
	v_fmac_f32_e32 v81, v18, v68
	v_add_f32_e32 v18, 0, v31
	s_waitcnt vmcnt(2)
	v_fmac_f32_e32 v82, v18, v68
	v_add_f32_e32 v18, 0, v32
	global_store_dword v[36:37], v69, off
	global_store_dword v[38:39], v70, off
	global_store_dword v[40:41], v71, off
	global_store_dword v[42:43], v72, off
	s_waitcnt vmcnt(5)
	v_fmac_f32_e32 v83, v18, v68
	v_add_f32_e32 v38, 0, v33
	v_lshl_add_u64 v[18:19], v[34:35], 0, s[0:1]
	v_add_u32_e32 v34, v0, v176
	global_store_dword v[44:45], v73, off
	global_store_dword v[46:47], v74, off
	global_store_dword v[48:49], v75, off
	global_store_dword v[50:51], v76, off
	global_store_dword v[52:53], v77, off
	global_store_dword v[54:55], v78, off
	global_store_dword v[56:57], v79, off
	global_store_dword v[58:59], v80, off
	global_store_dword v[60:61], v81, off
	global_store_dword v[62:63], v82, off
	global_store_dword v[64:65], v83, off
	v_lshl_add_u64 v[20:21], v[18:19], 0, v[96:97]
	s_waitcnt vmcnt(15)
	v_fmac_f32_e32 v84, v38, v68
	v_ashrrev_i32_e32 v35, 31, v34
	v_lshl_add_u64 v[22:23], v[18:19], 0, v[98:99]
	v_lshl_add_u64 v[24:25], v[18:19], 0, v[100:101]
	v_lshl_add_u64 v[26:27], v[18:19], 0, v[102:103]
	v_lshl_add_u64 v[28:29], v[18:19], 0, v[104:105]
	v_lshl_add_u64 v[30:31], v[18:19], 0, v[106:107]
	v_lshl_add_u64 v[32:33], v[18:19], 0, v[108:109]
	global_load_dword v50, v[20:21], off
	global_load_dword v51, v[22:23], off
	global_load_dword v52, v[24:25], off
	global_load_dword v53, v[26:27], off
	global_load_dword v54, v[28:29], off
	global_load_dword v55, v[30:31], off
	global_load_dword v56, v[32:33], off
	v_lshl_add_u64 v[34:35], v[34:35], 2, s[28:29]
	global_store_dword v[66:67], v84, off
	global_load_dword v0, v[34:35], off
	v_lshl_add_u64 v[34:35], v[18:19], 0, v[110:111]
	global_load_dword v57, v[34:35], off
	v_lshl_add_u64 v[38:39], v[18:19], 0, v[112:113]
	global_load_dword v58, v[38:39], off
	v_lshl_add_u64 v[40:41], v[18:19], 0, v[114:115]
	global_load_dword v59, v[40:41], off
	v_lshl_add_u64 v[42:43], v[18:19], 0, v[116:117]
	global_load_dword v60, v[42:43], off
	v_lshl_add_u64 v[44:45], v[18:19], 0, v[118:119]
	global_load_dword v61, v[44:45], off
	v_lshl_add_u64 v[46:47], v[18:19], 0, v[120:121]
	global_load_dword v62, v[46:47], off
	v_lshl_add_u64 v[48:49], v[18:19], 0, v[122:123]
	global_load_dword v63, v[48:49], off
	v_lshl_add_u64 v[18:19], v[18:19], 0, v[124:125]
	global_load_dword v64, v[18:19], off
	s_waitcnt vmcnt(8)
	v_fmac_f32_e32 v85, v2, v0
	v_add_f32_e32 v2, 0, v6
	v_fmac_f32_e32 v53, v2, v0
	v_add_f32_e32 v2, 0, v7
	v_fmac_f32_e32 v54, v2, v0
	v_add_f32_e32 v2, 0, v8
	v_fmac_f32_e32 v55, v2, v0
	v_add_f32_e32 v2, 0, v9
	v_fmac_f32_e32 v56, v2, v0
	v_add_f32_e32 v2, 0, v10
	s_waitcnt vmcnt(7)
	v_fmac_f32_e32 v57, v2, v0
	v_add_f32_e32 v2, 0, v11
	s_waitcnt vmcnt(6)
	v_fmac_f32_e32 v58, v2, v0
	v_add_f32_e32 v2, 0, v12
	s_waitcnt vmcnt(5)
	v_fmac_f32_e32 v59, v2, v0
	v_add_f32_e32 v2, 0, v13
	s_waitcnt vmcnt(4)
	v_fmac_f32_e32 v60, v2, v0
	v_add_f32_e32 v2, 0, v14
	s_waitcnt vmcnt(3)
	v_fmac_f32_e32 v61, v2, v0
	v_add_f32_e32 v2, 0, v15
	s_waitcnt vmcnt(2)
	v_fmac_f32_e32 v62, v2, v0
	v_add_f32_e32 v2, 0, v16
	s_waitcnt vmcnt(1)
	v_fmac_f32_e32 v63, v2, v0
	v_add_f32_e32 v2, 0, v17
	s_waitcnt vmcnt(0)
	v_fmac_f32_e32 v64, v2, v0
	v_fmac_f32_e32 v50, v3, v0
	v_fmac_f32_e32 v51, v4, v0
	v_fmac_f32_e32 v52, v5, v0
	global_store_dword v[36:37], v85, off offset:128
	global_store_dword v[20:21], v50, off
	global_store_dword v[22:23], v51, off
	global_store_dword v[24:25], v52, off
	global_store_dword v[26:27], v53, off
	global_store_dword v[28:29], v54, off
	global_store_dword v[30:31], v55, off
	global_store_dword v[32:33], v56, off
	global_store_dword v[34:35], v57, off
	global_store_dword v[38:39], v58, off
	global_store_dword v[40:41], v59, off
	global_store_dword v[42:43], v60, off
	global_store_dword v[44:45], v61, off
	global_store_dword v[46:47], v62, off
	global_store_dword v[48:49], v63, off
	global_store_dword v[18:19], v64, off
	s_cbranch_scc0 .LBB0_954
